# strategy 7 (instruction selection): cross-half row-max shuffle in the attention tiles via v_permlane32_swap instead of ds_bpermute; the LDS fragment reads are waited at the PV MFMAs, not before the so
# baseline (speedup 1.0000x reference)
.LBB0_508:
	v_add_u32_e32 v2, v154, v144
	v_add_u32_e32 v4, v154, v145
	ds_read_b128 v[122:125], v2 offset:8192
	ds_read_b128 v[118:121], v4 offset:8192
	v_add_u32_e32 v2, v154, v146
	v_add_u32_e32 v4, v154, v147
	ds_read_b128 v[126:129], v2 offset:8192
	ds_read_b128 v[114:117], v4 offset:8192
	s_andn2_b64 vcc, exec, s[70:71]
	s_cbranch_vccnz .LBB0_510
	s_nop 0
	v_max_f32_e32 v2, v19, v19
	v_max_f32_e32 v4, v18, v18
	v_max_f32_e32 v2, v4, v2
	v_max3_f32 v2, v2, v20, v21
	v_max3_f32 v2, v2, v22, v23
	v_max3_f32 v2, v2, v24, v25
	v_and_b32_e32 v5, 64, v161
	v_max3_f32 v2, v2, v26, v27
	v_xor_b32_e32 v4, 32, v161
	v_add_u32_e32 v5, 64, v5
	v_max3_f32 v2, v2, v28, v29
	v_cmp_lt_i32_e32 vcc, v4, v5
	v_max3_f32 v2, v2, v30, v31
	v_max3_f32 v2, v2, v32, v33
	v_cndmask_b32_e32 v4, v161, v4, vcc
	v_lshlrev_b32_e32 v4, 2, v4
	v_mov_b32_e32 v4, v2
	s_nop 1
	v_permlane32_swap_b32_e32 v4, v2
	s_nop 0
	v_readlane_b32 s70, v254, 29
	v_readlane_b32 s71, v254, 30
	v_max_f32_e32 v4, v4, v4
	v_max_f32_e32 v2, v2, v4
	v_mul_f32_e32 v2, 0x3fb8aa3b, v2
	v_max_f32_e32 v4, 0xf149f2ca, v2
	v_sub_f32_e32 v5, 0xf149f2ca, v4
	v_exp_f32_e32 v5, v5
	v_cmp_lt_f32_e32 vcc, s11, v2
	s_cmp_eq_u64 vcc, 0
	s_cselect_b64 vcc, -1, 0
	v_mul_f32_e32 v2, 0, v5
	v_cndmask_b32_e32 v141, v4, v162, vcc
	v_cndmask_b32_e64 v66, v2, 0, vcc
	v_fma_f32 v2, v33, s10, -v141
	v_exp_f32_e32 v2, v2
	v_fma_f32 v4, v32, s10, -v141
	v_exp_f32_e32 v4, v4
	v_fma_f32 v5, v31, s10, -v141
	v_exp_f32_e32 v5, v5
	v_cndmask_b32_e64 v33, 0, v2, s[70:71]
	v_readlane_b32 s70, v254, 31
	v_fma_f32 v6, v30, s10, -v141
	v_readlane_b32 s71, v254, 32
	v_exp_f32_e32 v6, v6
	v_fma_f32 v2, v29, s10, -v141
	v_cndmask_b32_e64 v32, 0, v4, s[70:71]
	v_readlane_b32 s70, v254, 33
	v_readlane_b32 s71, v254, 34
	v_exp_f32_e32 v2, v2
	v_fma_f32 v4, v28, s10, -v141
	v_cndmask_b32_e64 v31, 0, v5, s[70:71]
	v_readlane_b32 s70, v254, 44
	v_readlane_b32 s71, v254, 45
	v_fma_f32 v5, v27, s10, -v141
	v_exp_f32_e32 v5, v5
	v_cndmask_b32_e64 v30, 0, v6, s[70:71]
	v_fma_f32 v6, v26, s10, -v141
	v_exp_f32_e32 v6, v6
	v_exp_f32_e32 v4, v4
	v_readlane_b32 s70, v254, 48
	v_readlane_b32 s71, v254, 49
	v_cndmask_b32_e64 v26, 0, v6, s[16:17]
	v_fma_f32 v6, v22, s10, -v141
	v_cndmask_b32_e64 v29, 0, v2, s[70:71]
	v_cndmask_b32_e64 v27, 0, v5, s[14:15]
	v_fma_f32 v2, v25, s10, -v141
	v_fma_f32 v5, v23, s10, -v141
	v_exp_f32_e32 v6, v6
	v_cndmask_b32_e64 v28, 0, v4, s[12:13]
	v_exp_f32_e32 v2, v2
	v_fma_f32 v4, v24, s10, -v141
	v_exp_f32_e32 v5, v5
	v_exp_f32_e32 v4, v4
	v_cndmask_b32_e64 v22, 0, v6, s[24:25]
	v_fma_f32 v6, v18, s10, -v141
	v_cndmask_b32_e64 v25, 0, v2, s[18:19]
	v_cndmask_b32_e64 v23, 0, v5, s[22:23]
	v_fma_f32 v2, v21, s10, -v141
	v_fma_f32 v5, v19, s10, -v141
	v_exp_f32_e32 v6, v6
	v_cndmask_b32_e64 v24, 0, v4, s[20:21]
	v_exp_f32_e32 v2, v2
	v_fma_f32 v4, v20, s10, -v141
	v_exp_f32_e32 v5, v5
	v_exp_f32_e32 v4, v4
	v_cndmask_b32_e64 v18, 0, v6, s[34:35]
	v_cndmask_b32_e64 v21, 0, v2, s[26:27]
	v_cndmask_b32_e64 v19, 0, v5, s[30:31]
	v_add_f32_e32 v2, 0, v18
	v_cndmask_b32_e64 v20, 0, v4, s[28:29]
	v_add_f32_e32 v2, v19, v2
	v_add_f32_e32 v2, v20, v2
	v_add_f32_e32 v2, v21, v2
	v_add_f32_e32 v2, v22, v2
	v_add_f32_e32 v2, v23, v2
	v_add_f32_e32 v2, v24, v2
	v_add_f32_e32 v2, v25, v2
	v_add_f32_e32 v2, v26, v2
	v_add_f32_e32 v2, v27, v2
	v_add_f32_e32 v2, v28, v2
	v_add_f32_e32 v2, v29, v2
	v_add_f32_e32 v2, v30, v2
	v_add_f32_e32 v2, v31, v2
	v_add_f32_e32 v2, v32, v2
	v_mov_b32_e32 v67, v66
	v_mov_b32_e32 v68, v66
	v_mov_b32_e32 v69, v66
	v_mov_b32_e32 v70, v66
	v_mov_b32_e32 v71, v66
	v_mov_b32_e32 v72, v66
	v_mov_b32_e32 v73, v66
	v_mov_b32_e32 v74, v66
	v_mov_b32_e32 v75, v66
	v_mov_b32_e32 v76, v66
	v_mov_b32_e32 v77, v66
	v_mov_b32_e32 v78, v66
	v_mov_b32_e32 v79, v66
	v_mov_b32_e32 v80, v66
	v_mov_b32_e32 v81, v66
	v_add_f32_e32 v2, v33, v2
	v_cvt_pk_bf16_f32 v4, v18, v19
	v_cvt_pk_bf16_f32 v5, v20, v21
	v_cvt_pk_bf16_f32 v6, v22, v23
	v_cvt_pk_bf16_f32 v7, v24, v25
	v_cvt_pk_bf16_f32 v8, v26, v27
	v_cvt_pk_bf16_f32 v9, v28, v29
	v_cvt_pk_bf16_f32 v10, v30, v31
	v_cvt_pk_bf16_f32 v11, v32, v33
	v_mov_b64_e32 v[50:51], v[66:67]
	v_mov_b64_e32 v[52:53], v[68:69]
	v_mov_b64_e32 v[54:55], v[70:71]
	v_mov_b64_e32 v[56:57], v[72:73]
	v_mov_b64_e32 v[58:59], v[74:75]
	v_mov_b64_e32 v[60:61], v[76:77]
	v_mov_b64_e32 v[62:63], v[78:79]
	v_mov_b64_e32 v[64:65], v[80:81]
	s_waitcnt lgkmcnt(0)
	v_mfma_f32_32x32x16_bf16 v[34:49], v[98:101], v[4:7], v[66:81]
	v_add_f32_e32 v139, v66, v2
	v_mfma_f32_32x32x16_bf16 v[50:65], v[110:113], v[4:7], v[50:65]
	v_mfma_f32_32x32x16_bf16 v[34:49], v[102:105], v[8:11], v[34:49]
	v_mfma_f32_32x32x16_bf16 v[50:65], v[106:109], v[8:11], v[50:65]
	s_cmp_ge_i32 s92, s84
	s_cselect_b64 s[70:71], -1, 0
	s_cmp_lt_i32 s92, s84
	s_cbranch_scc0 .LBB0_511
	s_branch .LBB0_512

.LBB0_512:
	v_add_u32_e32 v2, v155, v144
	v_add_u32_e32 v4, v155, v145
	ds_read_b128 v[12:15], v2 offset:8192
	ds_read_b128 v[8:11], v4 offset:8192
	v_add_u32_e32 v2, v155, v146
	v_add_u32_e32 v4, v155, v147
	ds_read_b128 v[66:69], v2 offset:8192
	ds_read_b128 v[4:7], v4 offset:8192
	s_andn2_b64 vcc, exec, s[70:71]
	s_cbranch_vccnz .LBB0_516
	s_nop 1
	v_max_f32_e32 v2, v19, v19
	v_max_f32_e32 v16, v18, v18
	v_max_f32_e32 v2, v16, v2
	v_max3_f32 v2, v2, v20, v21
	v_max3_f32 v2, v2, v22, v23
	v_mbcnt_hi_u32_b32 v16, -1, v1
	v_max3_f32 v2, v2, v24, v25
	v_and_b32_e32 v70, 64, v16
	v_max3_f32 v2, v2, v26, v27
	v_xor_b32_e32 v17, 32, v16
	v_add_u32_e32 v70, 64, v70
	v_max3_f32 v2, v2, v28, v29
	v_cmp_lt_i32_e32 vcc, v17, v70
	v_max3_f32 v2, v2, v30, v31
	v_max3_f32 v2, v2, v32, v33
	v_cndmask_b32_e32 v16, v16, v17, vcc
	v_lshlrev_b32_e32 v16, 2, v16
	v_mov_b32_e32 v16, v2
	s_nop 1
	v_permlane32_swap_b32_e32 v16, v2
	s_nop 0
	v_max_f32_e32 v16, v16, v16
	v_max_f32_e32 v2, v2, v16
	v_mul_f32_e32 v2, 0x3fb8aa3b, v2
	v_add_f32_e32 v16, 0x41380000, v141
	v_cmp_gt_f32_e32 vcc, v2, v16
	s_cbranch_vccz .LBB0_515
	v_max_f32_e32 v2, v2, v2
	v_max_f32_e32 v16, v141, v141
	v_max_f32_e32 v16, v16, v2
	v_sub_f32_e32 v2, v141, v16
	v_exp_f32_e32 v2, v2
	v_mov_b32_e32 v141, v16
	v_pk_mul_f32 v[48:49], v[48:49], v[2:3] op_sel_hi:[1,0]
	v_pk_mul_f32 v[46:47], v[46:47], v[2:3] op_sel_hi:[1,0]
	v_pk_mul_f32 v[44:45], v[44:45], v[2:3] op_sel_hi:[1,0]
	v_pk_mul_f32 v[42:43], v[42:43], v[2:3] op_sel_hi:[1,0]
	v_pk_mul_f32 v[40:41], v[40:41], v[2:3] op_sel_hi:[1,0]
	v_pk_mul_f32 v[38:39], v[38:39], v[2:3] op_sel_hi:[1,0]
	v_pk_mul_f32 v[36:37], v[36:37], v[2:3] op_sel_hi:[1,0]
	v_pk_mul_f32 v[34:35], v[34:35], v[2:3] op_sel_hi:[1,0]
	v_pk_mul_f32 v[64:65], v[64:65], v[2:3] op_sel_hi:[1,0]
	v_pk_mul_f32 v[62:63], v[62:63], v[2:3] op_sel_hi:[1,0]
	v_pk_mul_f32 v[60:61], v[60:61], v[2:3] op_sel_hi:[1,0]
	v_pk_mul_f32 v[58:59], v[58:59], v[2:3] op_sel_hi:[1,0]
	v_pk_mul_f32 v[56:57], v[56:57], v[2:3] op_sel_hi:[1,0]
	v_pk_mul_f32 v[54:55], v[54:55], v[2:3] op_sel_hi:[1,0]
	v_pk_mul_f32 v[52:53], v[52:53], v[2:3] op_sel_hi:[1,0]
	v_pk_mul_f32 v[50:51], v[50:51], v[2:3] op_sel_hi:[1,0]
	v_mul_f32_e32 v139, v139, v2
.LBB0_515:
	v_fma_f32 v2, v33, s10, -v141
	v_exp_f32_e32 v33, v2
	v_fma_f32 v2, v32, s10, -v141
	v_exp_f32_e32 v32, v2
	v_fma_f32 v2, v31, s10, -v141
	v_exp_f32_e32 v31, v2
	v_fma_f32 v2, v30, s10, -v141
	v_exp_f32_e32 v30, v2
	v_fma_f32 v2, v29, s10, -v141
	v_exp_f32_e32 v29, v2
	v_fma_f32 v2, v28, s10, -v141
	v_exp_f32_e32 v28, v2
	v_fma_f32 v2, v27, s10, -v141
	v_exp_f32_e32 v27, v2
	v_fma_f32 v2, v26, s10, -v141
	v_exp_f32_e32 v26, v2
	v_fma_f32 v2, v25, s10, -v141
	v_exp_f32_e32 v25, v2
	v_fma_f32 v2, v24, s10, -v141
	v_fma_f32 v18, v18, s10, -v141
	v_exp_f32_e32 v24, v2
	v_fma_f32 v2, v23, s10, -v141
	v_fma_f32 v17, v19, s10, -v141
	v_exp_f32_e32 v18, v18
	v_exp_f32_e32 v23, v2
	v_fma_f32 v2, v22, s10, -v141
	v_fma_f32 v16, v20, s10, -v141
	v_exp_f32_e32 v19, v17
	v_exp_f32_e32 v22, v2
	v_fma_f32 v2, v21, s10, -v141
	v_exp_f32_e32 v20, v16
	v_exp_f32_e32 v21, v2
	v_add_f32_e32 v2, 0, v18
	v_add_f32_e32 v2, v19, v2
	v_add_f32_e32 v2, v20, v2
	v_add_f32_e32 v2, v21, v2
	v_add_f32_e32 v2, v22, v2
	v_add_f32_e32 v2, v23, v2
	v_add_f32_e32 v2, v24, v2
	v_add_f32_e32 v2, v25, v2
	v_add_f32_e32 v2, v26, v2
	v_add_f32_e32 v2, v27, v2
	v_add_f32_e32 v2, v28, v2
	v_add_f32_e32 v2, v29, v2
	v_add_f32_e32 v2, v30, v2
	v_add_f32_e32 v2, v31, v2
	v_add_f32_e32 v2, v32, v2
	v_add_f32_e32 v2, v33, v2
	v_cvt_pk_bf16_f32 v70, v18, v19
	v_cvt_pk_bf16_f32 v71, v20, v21
	v_cvt_pk_bf16_f32 v72, v22, v23
	v_cvt_pk_bf16_f32 v73, v24, v25
	v_cvt_pk_bf16_f32 v74, v26, v27
	v_cvt_pk_bf16_f32 v75, v28, v29
	v_cvt_pk_bf16_f32 v76, v30, v31
	v_cvt_pk_bf16_f32 v77, v32, v33
	s_waitcnt lgkmcnt(0)
	v_mfma_f32_32x32x16_bf16 v[34:49], v[98:101], v[70:73], v[34:49]
	v_add_f32_e32 v139, v139, v2
	v_mfma_f32_32x32x16_bf16 v[50:65], v[110:113], v[70:73], v[50:65]
	v_mfma_f32_32x32x16_bf16 v[34:49], v[102:105], v[74:77], v[34:49]
	v_mfma_f32_32x32x16_bf16 v[50:65], v[106:109], v[74:77], v[50:65]

.LBB0_518:
	v_add_u32_e32 v2, v156, v144
	s_waitcnt lgkmcnt(0)
	v_add_u32_e32 v4, v156, v145
	ds_read_b128 v[12:15], v2 offset:8192
	ds_read_b128 v[8:11], v4 offset:8192
	v_add_u32_e32 v2, v156, v146
	v_add_u32_e32 v4, v156, v147
	ds_read_b128 v[66:69], v2 offset:8192
	ds_read_b128 v[4:7], v4 offset:8192
	s_andn2_b64 vcc, exec, s[70:71]
	s_cbranch_vccnz .LBB0_522
	s_nop 0
	v_max_f32_e32 v2, v19, v19
	v_max_f32_e32 v16, v18, v18
	v_max_f32_e32 v2, v16, v2
	v_max3_f32 v2, v2, v20, v21
	v_max3_f32 v2, v2, v22, v23
	v_mbcnt_hi_u32_b32 v16, -1, v1
	v_max3_f32 v2, v2, v24, v25
	v_and_b32_e32 v70, 64, v16
	v_max3_f32 v2, v2, v26, v27
	v_xor_b32_e32 v17, 32, v16
	v_add_u32_e32 v70, 64, v70
	v_max3_f32 v2, v2, v28, v29
	v_cmp_lt_i32_e32 vcc, v17, v70
	v_max3_f32 v2, v2, v30, v31
	v_max3_f32 v2, v2, v32, v33
	v_cndmask_b32_e32 v16, v16, v17, vcc
	v_lshlrev_b32_e32 v16, 2, v16
	v_mov_b32_e32 v16, v2
	s_nop 1
	v_permlane32_swap_b32_e32 v16, v2
	s_nop 0
	v_max_f32_e32 v16, v16, v16
	v_max_f32_e32 v2, v2, v16
	v_mul_f32_e32 v2, 0x3fb8aa3b, v2
	v_add_f32_e32 v16, 0x41380000, v141
	v_cmp_gt_f32_e32 vcc, v2, v16
	s_cbranch_vccz .LBB0_521
	v_max_f32_e32 v2, v2, v2
	v_max_f32_e32 v16, v141, v141
	v_max_f32_e32 v16, v16, v2
	v_sub_f32_e32 v2, v141, v16
	v_exp_f32_e32 v2, v2
	v_mov_b32_e32 v141, v16
	v_pk_mul_f32 v[48:49], v[48:49], v[2:3] op_sel_hi:[1,0]
	v_pk_mul_f32 v[46:47], v[46:47], v[2:3] op_sel_hi:[1,0]
	v_pk_mul_f32 v[44:45], v[44:45], v[2:3] op_sel_hi:[1,0]
	v_pk_mul_f32 v[42:43], v[42:43], v[2:3] op_sel_hi:[1,0]
	v_pk_mul_f32 v[40:41], v[40:41], v[2:3] op_sel_hi:[1,0]
	v_pk_mul_f32 v[38:39], v[38:39], v[2:3] op_sel_hi:[1,0]
	v_pk_mul_f32 v[36:37], v[36:37], v[2:3] op_sel_hi:[1,0]
	v_pk_mul_f32 v[34:35], v[34:35], v[2:3] op_sel_hi:[1,0]
	v_pk_mul_f32 v[64:65], v[64:65], v[2:3] op_sel_hi:[1,0]
	v_pk_mul_f32 v[62:63], v[62:63], v[2:3] op_sel_hi:[1,0]
	v_pk_mul_f32 v[60:61], v[60:61], v[2:3] op_sel_hi:[1,0]
	v_pk_mul_f32 v[58:59], v[58:59], v[2:3] op_sel_hi:[1,0]
	v_pk_mul_f32 v[56:57], v[56:57], v[2:3] op_sel_hi:[1,0]
	v_pk_mul_f32 v[54:55], v[54:55], v[2:3] op_sel_hi:[1,0]
	v_pk_mul_f32 v[52:53], v[52:53], v[2:3] op_sel_hi:[1,0]
	v_pk_mul_f32 v[50:51], v[50:51], v[2:3] op_sel_hi:[1,0]
	v_mul_f32_e32 v139, v139, v2

.LBB0_524:
	v_add_u32_e32 v2, v157, v144
	s_waitcnt lgkmcnt(0)
	v_add_u32_e32 v4, v157, v145
	ds_read_b128 v[12:15], v2 offset:8192
	ds_read_b128 v[8:11], v4 offset:8192
	v_add_u32_e32 v2, v157, v146
	v_add_u32_e32 v4, v157, v147
	ds_read_b128 v[66:69], v2 offset:8192
	ds_read_b128 v[4:7], v4 offset:8192
	s_andn2_b64 vcc, exec, s[70:71]
	s_cbranch_vccnz .LBB0_528
	s_nop 0
	v_max_f32_e32 v2, v19, v19
	v_max_f32_e32 v16, v18, v18
	v_max_f32_e32 v2, v16, v2
	v_max3_f32 v2, v2, v20, v21
	v_max3_f32 v2, v2, v22, v23
	v_mbcnt_hi_u32_b32 v16, -1, v1
	v_max3_f32 v2, v2, v24, v25
	v_and_b32_e32 v70, 64, v16
	v_max3_f32 v2, v2, v26, v27
	v_xor_b32_e32 v17, 32, v16
	v_add_u32_e32 v70, 64, v70
	v_max3_f32 v2, v2, v28, v29
	v_cmp_lt_i32_e32 vcc, v17, v70
	v_max3_f32 v2, v2, v30, v31
	v_max3_f32 v2, v2, v32, v33
	v_cndmask_b32_e32 v16, v16, v17, vcc
	v_lshlrev_b32_e32 v16, 2, v16
	v_mov_b32_e32 v16, v2
	s_nop 1
	v_permlane32_swap_b32_e32 v16, v2
	s_nop 0
	v_max_f32_e32 v16, v16, v16
	v_max_f32_e32 v2, v2, v16
	v_mul_f32_e32 v2, 0x3fb8aa3b, v2
	v_add_f32_e32 v16, 0x41380000, v141
	v_cmp_gt_f32_e32 vcc, v2, v16
	s_cbranch_vccz .LBB0_527
	v_max_f32_e32 v2, v2, v2
	v_max_f32_e32 v16, v141, v141
	v_max_f32_e32 v16, v16, v2
	v_sub_f32_e32 v2, v141, v16
	v_exp_f32_e32 v2, v2
	v_mov_b32_e32 v141, v16
	v_pk_mul_f32 v[48:49], v[48:49], v[2:3] op_sel_hi:[1,0]
	v_pk_mul_f32 v[46:47], v[46:47], v[2:3] op_sel_hi:[1,0]
	v_pk_mul_f32 v[44:45], v[44:45], v[2:3] op_sel_hi:[1,0]
	v_pk_mul_f32 v[42:43], v[42:43], v[2:3] op_sel_hi:[1,0]
	v_pk_mul_f32 v[40:41], v[40:41], v[2:3] op_sel_hi:[1,0]
	v_pk_mul_f32 v[38:39], v[38:39], v[2:3] op_sel_hi:[1,0]
	v_pk_mul_f32 v[36:37], v[36:37], v[2:3] op_sel_hi:[1,0]
	v_pk_mul_f32 v[34:35], v[34:35], v[2:3] op_sel_hi:[1,0]
	v_pk_mul_f32 v[64:65], v[64:65], v[2:3] op_sel_hi:[1,0]
	v_pk_mul_f32 v[62:63], v[62:63], v[2:3] op_sel_hi:[1,0]
	v_pk_mul_f32 v[60:61], v[60:61], v[2:3] op_sel_hi:[1,0]
	v_pk_mul_f32 v[58:59], v[58:59], v[2:3] op_sel_hi:[1,0]
	v_pk_mul_f32 v[56:57], v[56:57], v[2:3] op_sel_hi:[1,0]
	v_pk_mul_f32 v[54:55], v[54:55], v[2:3] op_sel_hi:[1,0]
	v_pk_mul_f32 v[52:53], v[52:53], v[2:3] op_sel_hi:[1,0]
	v_pk_mul_f32 v[50:51], v[50:51], v[2:3] op_sel_hi:[1,0]
	v_mul_f32_e32 v139, v139, v2

.LBB0_547:
	ds_read_b128 v[126:129], v37 offset:8192
	ds_read_b128 v[122:125], v36 offset:8192
	ds_read_b128 v[118:121], v35 offset:8192
	ds_read_b128 v[114:117], v34 offset:8192
	s_andn2_b64 vcc, exec, s[84:85]
	s_cbranch_vccnz .LBB0_549
	s_nop 4
	v_max_f32_e32 v2, v19, v19
	v_max_f32_e32 v4, v18, v18
	v_max_f32_e32 v2, v4, v2
	v_max3_f32 v2, v2, v20, v21
	v_max3_f32 v2, v2, v22, v23
	v_mbcnt_hi_u32_b32 v4, -1, v1
	v_max3_f32 v2, v2, v24, v25
	v_and_b32_e32 v6, 64, v4
	v_max3_f32 v2, v2, v26, v27
	v_xor_b32_e32 v5, 32, v4
	v_add_u32_e32 v6, 64, v6
	v_max3_f32 v2, v2, v28, v29
	v_cmp_lt_i32_e32 vcc, v5, v6
	v_max3_f32 v2, v2, v30, v31
	v_max3_f32 v2, v2, v32, v33
	v_cndmask_b32_e32 v4, v4, v5, vcc
	v_lshlrev_b32_e32 v4, 2, v4
	v_mov_b32_e32 v4, v2
	s_nop 1
	v_permlane32_swap_b32_e32 v4, v2
	s_nop 0
	v_readlane_b32 s84, v254, 29
	v_readlane_b32 s85, v254, 30
	v_max_f32_e32 v4, v4, v4
	v_max_f32_e32 v2, v2, v4
	v_mul_f32_e32 v2, 0x3fb8aa3b, v2
	v_max_f32_e32 v4, 0xf149f2ca, v2
	v_sub_f32_e32 v5, 0xf149f2ca, v4
	v_exp_f32_e32 v5, v5
	v_cmp_lt_f32_e32 vcc, s11, v2
	s_cmp_eq_u64 vcc, 0
	s_cselect_b64 vcc, -1, 0
	v_mul_f32_e32 v2, 0, v5
	v_cndmask_b32_e32 v141, v4, v162, vcc
	v_cndmask_b32_e64 v66, v2, 0, vcc
	v_fma_f32 v2, v33, s10, -v141
	v_exp_f32_e32 v2, v2
	v_fma_f32 v4, v32, s10, -v141
	v_exp_f32_e32 v4, v4
	v_fma_f32 v5, v31, s10, -v141
	v_exp_f32_e32 v5, v5
	v_cndmask_b32_e64 v33, 0, v2, s[84:85]
	v_readlane_b32 s84, v254, 31
	v_fma_f32 v6, v30, s10, -v141
	v_readlane_b32 s85, v254, 32
	v_exp_f32_e32 v6, v6
	v_fma_f32 v2, v29, s10, -v141
	v_cndmask_b32_e64 v32, 0, v4, s[84:85]
	v_readlane_b32 s84, v254, 33
	v_readlane_b32 s85, v254, 34
	v_exp_f32_e32 v2, v2
	v_fma_f32 v4, v28, s10, -v141
	v_cndmask_b32_e64 v31, 0, v5, s[84:85]
	v_readlane_b32 s84, v254, 44
	v_readlane_b32 s85, v254, 45
	v_fma_f32 v5, v27, s10, -v141
	v_exp_f32_e32 v5, v5
	v_cndmask_b32_e64 v30, 0, v6, s[84:85]
	v_fma_f32 v6, v26, s10, -v141
	v_exp_f32_e32 v6, v6
	v_exp_f32_e32 v4, v4
	v_readlane_b32 s84, v254, 48
	v_readlane_b32 s85, v254, 49
	v_cndmask_b32_e64 v26, 0, v6, s[16:17]
	v_fma_f32 v6, v22, s10, -v141
	v_cndmask_b32_e64 v29, 0, v2, s[84:85]
	v_cndmask_b32_e64 v27, 0, v5, s[14:15]
	v_fma_f32 v2, v25, s10, -v141
	v_fma_f32 v5, v23, s10, -v141
	v_exp_f32_e32 v6, v6
	v_cndmask_b32_e64 v28, 0, v4, s[12:13]
	v_exp_f32_e32 v2, v2
	v_fma_f32 v4, v24, s10, -v141
	v_exp_f32_e32 v5, v5
	v_exp_f32_e32 v4, v4
	v_cndmask_b32_e64 v22, 0, v6, s[24:25]
	v_fma_f32 v6, v18, s10, -v141
	v_cndmask_b32_e64 v25, 0, v2, s[18:19]
	v_cndmask_b32_e64 v23, 0, v5, s[22:23]
	v_fma_f32 v2, v21, s10, -v141
	v_fma_f32 v5, v19, s10, -v141
	v_exp_f32_e32 v6, v6
	v_cndmask_b32_e64 v24, 0, v4, s[20:21]
	v_exp_f32_e32 v2, v2
	v_fma_f32 v4, v20, s10, -v141
	v_exp_f32_e32 v5, v5
	v_exp_f32_e32 v4, v4
	v_cndmask_b32_e64 v18, 0, v6, s[34:35]
	v_cndmask_b32_e64 v21, 0, v2, s[26:27]
	v_cndmask_b32_e64 v19, 0, v5, s[30:31]
	v_add_f32_e32 v2, 0, v18
	v_cndmask_b32_e64 v20, 0, v4, s[28:29]
	v_add_f32_e32 v2, v19, v2
	v_add_f32_e32 v2, v20, v2
	v_add_f32_e32 v2, v21, v2
	v_add_f32_e32 v2, v22, v2
	v_add_f32_e32 v2, v23, v2
	v_add_f32_e32 v2, v24, v2
	v_add_f32_e32 v2, v25, v2
	v_add_f32_e32 v2, v26, v2
	v_add_f32_e32 v2, v27, v2
	v_add_f32_e32 v2, v28, v2
	v_add_f32_e32 v2, v29, v2
	v_add_f32_e32 v2, v30, v2
	v_add_f32_e32 v2, v31, v2
	v_add_f32_e32 v2, v32, v2
	v_mov_b32_e32 v67, v66
	v_mov_b32_e32 v68, v66
	v_mov_b32_e32 v69, v66
	v_mov_b32_e32 v70, v66
	v_mov_b32_e32 v71, v66
	v_mov_b32_e32 v72, v66
	v_mov_b32_e32 v73, v66
	v_mov_b32_e32 v74, v66
	v_mov_b32_e32 v75, v66
	v_mov_b32_e32 v76, v66
	v_mov_b32_e32 v77, v66
	v_mov_b32_e32 v78, v66
	v_mov_b32_e32 v79, v66
	v_mov_b32_e32 v80, v66
	v_mov_b32_e32 v81, v66
	v_add_f32_e32 v2, v33, v2
	v_cvt_pk_bf16_f32 v4, v18, v19
	v_cvt_pk_bf16_f32 v5, v20, v21
	v_cvt_pk_bf16_f32 v6, v22, v23
	v_cvt_pk_bf16_f32 v7, v24, v25
	v_cvt_pk_bf16_f32 v8, v26, v27
	v_cvt_pk_bf16_f32 v9, v28, v29
	v_cvt_pk_bf16_f32 v10, v30, v31
	v_cvt_pk_bf16_f32 v11, v32, v33
	v_mov_b64_e32 v[50:51], v[66:67]
	v_mov_b64_e32 v[52:53], v[68:69]
	v_mov_b64_e32 v[54:55], v[70:71]
	v_mov_b64_e32 v[56:57], v[72:73]
	v_mov_b64_e32 v[58:59], v[74:75]
	v_mov_b64_e32 v[60:61], v[76:77]
	v_mov_b64_e32 v[62:63], v[78:79]
	v_mov_b64_e32 v[64:65], v[80:81]
	s_waitcnt lgkmcnt(0)
	v_mfma_f32_32x32x16_bf16 v[34:49], v[98:101], v[4:7], v[66:81]
	v_add_f32_e32 v139, v66, v2
	v_mfma_f32_32x32x16_bf16 v[50:65], v[110:113], v[4:7], v[50:65]
	v_mfma_f32_32x32x16_bf16 v[34:49], v[102:105], v[8:11], v[34:49]
	v_mfma_f32_32x32x16_bf16 v[50:65], v[106:109], v[8:11], v[50:65]
	s_cmp_ge_i32 s92, s86
	s_cselect_b64 s[84:85], -1, 0
	s_cmp_lt_i32 s92, s86
	s_cbranch_scc0 .LBB0_550
	s_branch .LBB0_551

.LBB0_551:
	v_add_u32_e32 v2, v155, v144
	v_add_u32_e32 v4, v155, v145
	ds_read_b128 v[12:15], v2 offset:8192
	ds_read_b128 v[8:11], v4 offset:8192
	v_add_u32_e32 v2, v155, v146
	v_add_u32_e32 v4, v155, v147
	ds_read_b128 v[66:69], v2 offset:8192
	ds_read_b128 v[4:7], v4 offset:8192
	s_andn2_b64 vcc, exec, s[84:85]
	s_cbranch_vccnz .LBB0_555
	s_nop 1
	v_max_f32_e32 v2, v19, v19
	v_max_f32_e32 v16, v18, v18
	v_max_f32_e32 v2, v16, v2
	v_max3_f32 v2, v2, v20, v21
	v_max3_f32 v2, v2, v22, v23
	v_mbcnt_hi_u32_b32 v16, -1, v1
	v_max3_f32 v2, v2, v24, v25
	v_and_b32_e32 v70, 64, v16
	v_max3_f32 v2, v2, v26, v27
	v_xor_b32_e32 v17, 32, v16
	v_add_u32_e32 v70, 64, v70
	v_max3_f32 v2, v2, v28, v29
	v_cmp_lt_i32_e32 vcc, v17, v70
	v_max3_f32 v2, v2, v30, v31
	v_max3_f32 v2, v2, v32, v33
	v_cndmask_b32_e32 v16, v16, v17, vcc
	v_lshlrev_b32_e32 v16, 2, v16
	v_mov_b32_e32 v16, v2
	s_nop 1
	v_permlane32_swap_b32_e32 v16, v2
	s_nop 0
	v_max_f32_e32 v16, v16, v16
	v_max_f32_e32 v2, v2, v16
	v_mul_f32_e32 v2, 0x3fb8aa3b, v2
	v_add_f32_e32 v16, 0x41380000, v141
	v_cmp_gt_f32_e32 vcc, v2, v16
	s_cbranch_vccz .LBB0_554
	v_max_f32_e32 v2, v2, v2
	v_max_f32_e32 v16, v141, v141
	v_max_f32_e32 v16, v16, v2
	v_sub_f32_e32 v2, v141, v16
	v_exp_f32_e32 v2, v2
	v_mov_b32_e32 v141, v16
	v_pk_mul_f32 v[48:49], v[48:49], v[2:3] op_sel_hi:[1,0]
	v_pk_mul_f32 v[46:47], v[46:47], v[2:3] op_sel_hi:[1,0]
	v_pk_mul_f32 v[44:45], v[44:45], v[2:3] op_sel_hi:[1,0]
	v_pk_mul_f32 v[42:43], v[42:43], v[2:3] op_sel_hi:[1,0]
	v_pk_mul_f32 v[40:41], v[40:41], v[2:3] op_sel_hi:[1,0]
	v_pk_mul_f32 v[38:39], v[38:39], v[2:3] op_sel_hi:[1,0]
	v_pk_mul_f32 v[36:37], v[36:37], v[2:3] op_sel_hi:[1,0]
	v_pk_mul_f32 v[34:35], v[34:35], v[2:3] op_sel_hi:[1,0]
	v_pk_mul_f32 v[64:65], v[64:65], v[2:3] op_sel_hi:[1,0]
	v_pk_mul_f32 v[62:63], v[62:63], v[2:3] op_sel_hi:[1,0]
	v_pk_mul_f32 v[60:61], v[60:61], v[2:3] op_sel_hi:[1,0]
	v_pk_mul_f32 v[58:59], v[58:59], v[2:3] op_sel_hi:[1,0]
	v_pk_mul_f32 v[56:57], v[56:57], v[2:3] op_sel_hi:[1,0]
	v_pk_mul_f32 v[54:55], v[54:55], v[2:3] op_sel_hi:[1,0]
	v_pk_mul_f32 v[52:53], v[52:53], v[2:3] op_sel_hi:[1,0]
	v_pk_mul_f32 v[50:51], v[50:51], v[2:3] op_sel_hi:[1,0]
	v_mul_f32_e32 v139, v139, v2

.LBB0_557:
	v_add_u32_e32 v2, v156, v144
	s_waitcnt lgkmcnt(0)
	v_add_u32_e32 v4, v156, v145
	ds_read_b128 v[12:15], v2 offset:8192
	ds_read_b128 v[8:11], v4 offset:8192
	v_add_u32_e32 v2, v156, v146
	v_add_u32_e32 v4, v156, v147
	ds_read_b128 v[66:69], v2 offset:8192
	ds_read_b128 v[4:7], v4 offset:8192
	s_andn2_b64 vcc, exec, s[84:85]
	s_cbranch_vccnz .LBB0_561
	s_nop 0
	v_max_f32_e32 v2, v19, v19
	v_max_f32_e32 v16, v18, v18
	v_max_f32_e32 v2, v16, v2
	v_max3_f32 v2, v2, v20, v21
	v_max3_f32 v2, v2, v22, v23
	v_mbcnt_hi_u32_b32 v16, -1, v1
	v_max3_f32 v2, v2, v24, v25
	v_and_b32_e32 v70, 64, v16
	v_max3_f32 v2, v2, v26, v27
	v_xor_b32_e32 v17, 32, v16
	v_add_u32_e32 v70, 64, v70
	v_max3_f32 v2, v2, v28, v29
	v_cmp_lt_i32_e32 vcc, v17, v70
	v_max3_f32 v2, v2, v30, v31
	v_max3_f32 v2, v2, v32, v33
	v_cndmask_b32_e32 v16, v16, v17, vcc
	v_lshlrev_b32_e32 v16, 2, v16
	v_mov_b32_e32 v16, v2
	s_nop 1
	v_permlane32_swap_b32_e32 v16, v2
	s_nop 0
	v_max_f32_e32 v16, v16, v16
	v_max_f32_e32 v2, v2, v16
	v_mul_f32_e32 v2, 0x3fb8aa3b, v2
	v_add_f32_e32 v16, 0x41380000, v141
	v_cmp_gt_f32_e32 vcc, v2, v16
	s_cbranch_vccz .LBB0_560
	v_max_f32_e32 v2, v2, v2
	v_max_f32_e32 v16, v141, v141
	v_max_f32_e32 v16, v16, v2
	v_sub_f32_e32 v2, v141, v16
	v_exp_f32_e32 v2, v2
	v_mov_b32_e32 v141, v16
	v_pk_mul_f32 v[48:49], v[48:49], v[2:3] op_sel_hi:[1,0]
	v_pk_mul_f32 v[46:47], v[46:47], v[2:3] op_sel_hi:[1,0]
	v_pk_mul_f32 v[44:45], v[44:45], v[2:3] op_sel_hi:[1,0]
	v_pk_mul_f32 v[42:43], v[42:43], v[2:3] op_sel_hi:[1,0]
	v_pk_mul_f32 v[40:41], v[40:41], v[2:3] op_sel_hi:[1,0]
	v_pk_mul_f32 v[38:39], v[38:39], v[2:3] op_sel_hi:[1,0]
	v_pk_mul_f32 v[36:37], v[36:37], v[2:3] op_sel_hi:[1,0]
	v_pk_mul_f32 v[34:35], v[34:35], v[2:3] op_sel_hi:[1,0]
	v_pk_mul_f32 v[64:65], v[64:65], v[2:3] op_sel_hi:[1,0]
	v_pk_mul_f32 v[62:63], v[62:63], v[2:3] op_sel_hi:[1,0]
	v_pk_mul_f32 v[60:61], v[60:61], v[2:3] op_sel_hi:[1,0]
	v_pk_mul_f32 v[58:59], v[58:59], v[2:3] op_sel_hi:[1,0]
	v_pk_mul_f32 v[56:57], v[56:57], v[2:3] op_sel_hi:[1,0]
	v_pk_mul_f32 v[54:55], v[54:55], v[2:3] op_sel_hi:[1,0]
	v_pk_mul_f32 v[52:53], v[52:53], v[2:3] op_sel_hi:[1,0]
	v_pk_mul_f32 v[50:51], v[50:51], v[2:3] op_sel_hi:[1,0]
	v_mul_f32_e32 v139, v139, v2

.LBB0_563:
	v_add_u32_e32 v2, v157, v144
	s_waitcnt lgkmcnt(0)
	v_add_u32_e32 v4, v157, v145
	ds_read_b128 v[12:15], v2 offset:8192
	ds_read_b128 v[8:11], v4 offset:8192
	v_add_u32_e32 v2, v157, v146
	v_add_u32_e32 v4, v157, v147
	ds_read_b128 v[66:69], v2 offset:8192
	ds_read_b128 v[4:7], v4 offset:8192
	s_andn2_b64 vcc, exec, s[84:85]
	s_cbranch_vccnz .LBB0_567
	s_nop 0
	v_max_f32_e32 v2, v19, v19
	v_max_f32_e32 v16, v18, v18
	v_max_f32_e32 v2, v16, v2
	v_max3_f32 v2, v2, v20, v21
	v_max3_f32 v2, v2, v22, v23
	v_mbcnt_hi_u32_b32 v16, -1, v1
	v_max3_f32 v2, v2, v24, v25
	v_and_b32_e32 v70, 64, v16
	v_max3_f32 v2, v2, v26, v27
	v_xor_b32_e32 v17, 32, v16
	v_add_u32_e32 v70, 64, v70
	v_max3_f32 v2, v2, v28, v29
	v_cmp_lt_i32_e32 vcc, v17, v70
	v_max3_f32 v2, v2, v30, v31
	v_max3_f32 v2, v2, v32, v33
	v_cndmask_b32_e32 v16, v16, v17, vcc
	v_lshlrev_b32_e32 v16, 2, v16
	v_mov_b32_e32 v16, v2
	s_nop 1
	v_permlane32_swap_b32_e32 v16, v2
	s_nop 0
	v_max_f32_e32 v16, v16, v16
	v_max_f32_e32 v2, v2, v16
	v_mul_f32_e32 v2, 0x3fb8aa3b, v2
	v_add_f32_e32 v16, 0x41380000, v141
	v_cmp_gt_f32_e32 vcc, v2, v16
	s_cbranch_vccz .LBB0_566
	v_max_f32_e32 v2, v2, v2
	v_max_f32_e32 v16, v141, v141
	v_max_f32_e32 v16, v16, v2
	v_sub_f32_e32 v2, v141, v16
	v_exp_f32_e32 v2, v2
	v_mov_b32_e32 v141, v16
	v_pk_mul_f32 v[48:49], v[48:49], v[2:3] op_sel_hi:[1,0]
	v_pk_mul_f32 v[46:47], v[46:47], v[2:3] op_sel_hi:[1,0]
	v_pk_mul_f32 v[44:45], v[44:45], v[2:3] op_sel_hi:[1,0]
	v_pk_mul_f32 v[42:43], v[42:43], v[2:3] op_sel_hi:[1,0]
	v_pk_mul_f32 v[40:41], v[40:41], v[2:3] op_sel_hi:[1,0]
	v_pk_mul_f32 v[38:39], v[38:39], v[2:3] op_sel_hi:[1,0]
	v_pk_mul_f32 v[36:37], v[36:37], v[2:3] op_sel_hi:[1,0]
	v_pk_mul_f32 v[34:35], v[34:35], v[2:3] op_sel_hi:[1,0]
	v_pk_mul_f32 v[64:65], v[64:65], v[2:3] op_sel_hi:[1,0]
	v_pk_mul_f32 v[62:63], v[62:63], v[2:3] op_sel_hi:[1,0]
	v_pk_mul_f32 v[60:61], v[60:61], v[2:3] op_sel_hi:[1,0]
	v_pk_mul_f32 v[58:59], v[58:59], v[2:3] op_sel_hi:[1,0]
	v_pk_mul_f32 v[56:57], v[56:57], v[2:3] op_sel_hi:[1,0]
	v_pk_mul_f32 v[54:55], v[54:55], v[2:3] op_sel_hi:[1,0]
	v_pk_mul_f32 v[52:53], v[52:53], v[2:3] op_sel_hi:[1,0]
	v_pk_mul_f32 v[50:51], v[50:51], v[2:3] op_sel_hi:[1,0]
	v_mul_f32_e32 v139, v139, v2

.LBB0_586:
	ds_read_b128 v[126:129], v159 offset:8192
	ds_read_b128 v[122:125], v158 offset:8192
	ds_read_b128 v[118:121], v157 offset:8192
	ds_read_b128 v[114:117], v156 offset:8192
	s_andn2_b64 vcc, exec, s[86:87]
	v_mbcnt_hi_u32_b32 v137, -1, v1
	s_cbranch_vccnz .LBB0_588
	s_nop 4
	v_max_f32_e32 v2, v19, v19
	v_max_f32_e32 v4, v18, v18
	v_max_f32_e32 v2, v4, v2
	v_max3_f32 v2, v2, v20, v21
	v_max3_f32 v2, v2, v22, v23
	v_mbcnt_hi_u32_b32 v4, -1, v1
	v_max3_f32 v2, v2, v24, v25
	v_and_b32_e32 v6, 64, v4
	v_max3_f32 v2, v2, v26, v27
	v_xor_b32_e32 v5, 32, v4
	v_add_u32_e32 v6, 64, v6
	v_max3_f32 v2, v2, v28, v29
	v_cmp_lt_i32_e32 vcc, v5, v6
	v_max3_f32 v2, v2, v30, v31
	v_max3_f32 v2, v2, v32, v33
	v_cndmask_b32_e32 v4, v4, v5, vcc
	v_lshlrev_b32_e32 v4, 2, v4
	v_mov_b32_e32 v4, v2
	s_nop 1
	v_permlane32_swap_b32_e32 v4, v2
	s_nop 0
	s_mov_b32 s86, 0xf149f2ca
	v_max_f32_e32 v4, v4, v4
	v_max_f32_e32 v2, v2, v4
	v_mul_f32_e32 v2, 0x3fb8aa3b, v2
	v_max_f32_e32 v4, 0xf149f2ca, v2
	v_sub_f32_e32 v5, 0xf149f2ca, v4
	v_exp_f32_e32 v5, v5
	v_cmp_lt_f32_e32 vcc, s86, v2
	s_cmp_eq_u64 vcc, 0
	s_cselect_b64 vcc, -1, 0
	v_mul_f32_e32 v2, 0, v5
	v_cndmask_b32_e32 v162, v4, v160, vcc
	v_cndmask_b32_e64 v66, v2, 0, vcc
	v_fma_f32 v2, v33, s5, -v162
	v_exp_f32_e32 v2, v2
	v_fma_f32 v4, v32, s5, -v162
	v_exp_f32_e32 v4, v4
	v_fma_f32 v6, v30, s5, -v162
	v_readlane_b32 s86, v254, 29
	v_fma_f32 v5, v31, s5, -v162
	v_exp_f32_e32 v6, v6
	v_readlane_b32 s87, v254, 30
	v_exp_f32_e32 v5, v5
	v_mov_b32_e32 v67, v66
	v_cndmask_b32_e64 v33, 0, v2, s[86:87]
	v_readlane_b32 s86, v254, 31
	v_readlane_b32 s87, v254, 32
	v_cndmask_b32_e64 v30, 0, v6, s[8:9]
	v_fma_f32 v6, v26, s5, -v162
	v_cndmask_b32_e64 v32, 0, v4, s[86:87]
	v_readlane_b32 s86, v254, 33
	v_readlane_b32 s87, v254, 34
	v_fma_f32 v2, v29, s5, -v162
	v_exp_f32_e32 v6, v6
	v_cndmask_b32_e64 v31, 0, v5, s[86:87]
	v_fma_f32 v5, v27, s5, -v162
	v_exp_f32_e32 v2, v2
	v_fma_f32 v4, v28, s5, -v162
	v_exp_f32_e32 v5, v5
	v_exp_f32_e32 v4, v4
	v_cndmask_b32_e64 v26, 0, v6, s[16:17]
	v_fma_f32 v6, v22, s5, -v162
	v_cndmask_b32_e64 v29, 0, v2, s[10:11]
	v_cndmask_b32_e64 v27, 0, v5, s[14:15]
	v_fma_f32 v2, v25, s5, -v162
	v_fma_f32 v5, v23, s5, -v162
	v_exp_f32_e32 v6, v6
	v_cndmask_b32_e64 v28, 0, v4, s[12:13]
	v_exp_f32_e32 v2, v2
	v_fma_f32 v4, v24, s5, -v162
	v_exp_f32_e32 v5, v5
	v_exp_f32_e32 v4, v4
	v_cndmask_b32_e64 v22, 0, v6, s[24:25]
	v_fma_f32 v6, v18, s5, -v162
	v_cndmask_b32_e64 v25, 0, v2, s[18:19]
	v_cndmask_b32_e64 v23, 0, v5, s[22:23]
	v_fma_f32 v2, v21, s5, -v162
	v_fma_f32 v5, v19, s5, -v162
	v_exp_f32_e32 v6, v6
	v_cndmask_b32_e64 v24, 0, v4, s[20:21]
	v_exp_f32_e32 v2, v2
	v_fma_f32 v4, v20, s5, -v162
	v_exp_f32_e32 v5, v5
	v_exp_f32_e32 v4, v4
	v_cndmask_b32_e64 v18, 0, v6, s[34:35]
	v_cndmask_b32_e64 v21, 0, v2, s[26:27]
	v_cndmask_b32_e64 v19, 0, v5, s[30:31]
	v_add_f32_e32 v2, 0, v18
	v_cndmask_b32_e64 v20, 0, v4, s[28:29]
	v_add_f32_e32 v2, v19, v2
	v_add_f32_e32 v2, v20, v2
	v_add_f32_e32 v2, v21, v2
	v_add_f32_e32 v2, v22, v2
	v_add_f32_e32 v2, v23, v2
	v_add_f32_e32 v2, v24, v2
	v_add_f32_e32 v2, v25, v2
	v_add_f32_e32 v2, v26, v2
	v_add_f32_e32 v2, v27, v2
	v_add_f32_e32 v2, v28, v2
	v_add_f32_e32 v2, v29, v2
	v_add_f32_e32 v2, v30, v2
	v_add_f32_e32 v2, v31, v2
	v_add_f32_e32 v2, v32, v2
	v_mov_b32_e32 v68, v66
	v_mov_b32_e32 v69, v66
	v_mov_b32_e32 v70, v66
	v_mov_b32_e32 v71, v66
	v_mov_b32_e32 v72, v66
	v_mov_b32_e32 v73, v66
	v_mov_b32_e32 v74, v66
	v_mov_b32_e32 v75, v66
	v_mov_b32_e32 v76, v66
	v_mov_b32_e32 v77, v66
	v_mov_b32_e32 v78, v66
	v_mov_b32_e32 v79, v66
	v_mov_b32_e32 v80, v66
	v_mov_b32_e32 v81, v66
	v_add_f32_e32 v2, v33, v2
	v_cvt_pk_bf16_f32 v4, v18, v19
	v_cvt_pk_bf16_f32 v5, v20, v21
	v_cvt_pk_bf16_f32 v6, v22, v23
	v_cvt_pk_bf16_f32 v7, v24, v25
	v_cvt_pk_bf16_f32 v8, v26, v27
	v_cvt_pk_bf16_f32 v9, v28, v29
	v_cvt_pk_bf16_f32 v10, v30, v31
	v_cvt_pk_bf16_f32 v11, v32, v33
	v_mov_b64_e32 v[50:51], v[66:67]
	v_mov_b64_e32 v[52:53], v[68:69]
	v_mov_b64_e32 v[54:55], v[70:71]
	v_mov_b64_e32 v[56:57], v[72:73]
	v_mov_b64_e32 v[58:59], v[74:75]
	v_mov_b64_e32 v[60:61], v[76:77]
	v_mov_b64_e32 v[62:63], v[78:79]
	v_mov_b64_e32 v[64:65], v[80:81]
	s_waitcnt lgkmcnt(0)
	v_mfma_f32_32x32x16_bf16 v[34:49], v[98:101], v[4:7], v[66:81]
	v_add_f32_e32 v161, v66, v2
	v_mfma_f32_32x32x16_bf16 v[50:65], v[110:113], v[4:7], v[50:65]
	v_mfma_f32_32x32x16_bf16 v[34:49], v[102:105], v[8:11], v[34:49]
	v_mfma_f32_32x32x16_bf16 v[50:65], v[106:109], v[8:11], v[50:65]
	s_cmp_ge_i32 s94, s88
	s_cselect_b64 s[86:87], -1, 0
	s_cmp_lt_i32 s94, s88
	s_cbranch_scc0 .LBB0_589
	s_branch .LBB0_590

.LBB0_590:
	v_add_u32_e32 v2, v150, v141
	v_add_u32_e32 v4, v150, v142
	ds_read_b128 v[12:15], v2 offset:8192
	ds_read_b128 v[8:11], v4 offset:8192
	v_add_u32_e32 v2, v150, v143
	v_add_u32_e32 v4, v150, v144
	ds_read_b128 v[66:69], v2 offset:8192
	ds_read_b128 v[4:7], v4 offset:8192
	s_andn2_b64 vcc, exec, s[86:87]
	s_cbranch_vccnz .LBB0_594
	s_nop 1
	v_max_f32_e32 v2, v19, v19
	v_max_f32_e32 v16, v18, v18
	v_max_f32_e32 v2, v16, v2
	v_max3_f32 v2, v2, v20, v21
	v_max3_f32 v2, v2, v22, v23
	v_mbcnt_hi_u32_b32 v16, -1, v1
	v_max3_f32 v2, v2, v24, v25
	v_and_b32_e32 v70, 64, v16
	v_max3_f32 v2, v2, v26, v27
	v_xor_b32_e32 v17, 32, v16
	v_add_u32_e32 v70, 64, v70
	v_max3_f32 v2, v2, v28, v29
	v_cmp_lt_i32_e32 vcc, v17, v70
	v_max3_f32 v2, v2, v30, v31
	v_max3_f32 v2, v2, v32, v33
	v_cndmask_b32_e32 v16, v16, v17, vcc
	v_lshlrev_b32_e32 v16, 2, v16
	v_mov_b32_e32 v16, v2
	s_nop 1
	v_permlane32_swap_b32_e32 v16, v2
	s_nop 0
	v_max_f32_e32 v16, v16, v16
	v_max_f32_e32 v2, v2, v16
	v_mul_f32_e32 v2, 0x3fb8aa3b, v2
	v_add_f32_e32 v16, 0x41380000, v162
	v_cmp_gt_f32_e32 vcc, v2, v16
	s_cbranch_vccz .LBB0_593
	v_max_f32_e32 v2, v2, v2
	v_max_f32_e32 v16, v162, v162
	v_max_f32_e32 v16, v16, v2
	v_sub_f32_e32 v2, v162, v16
	v_exp_f32_e32 v2, v2
	v_mov_b32_e32 v162, v16
	v_pk_mul_f32 v[48:49], v[48:49], v[2:3] op_sel_hi:[1,0]
	v_pk_mul_f32 v[46:47], v[46:47], v[2:3] op_sel_hi:[1,0]
	v_pk_mul_f32 v[44:45], v[44:45], v[2:3] op_sel_hi:[1,0]
	v_pk_mul_f32 v[42:43], v[42:43], v[2:3] op_sel_hi:[1,0]
	v_pk_mul_f32 v[40:41], v[40:41], v[2:3] op_sel_hi:[1,0]
	v_pk_mul_f32 v[38:39], v[38:39], v[2:3] op_sel_hi:[1,0]
	v_pk_mul_f32 v[36:37], v[36:37], v[2:3] op_sel_hi:[1,0]
	v_pk_mul_f32 v[34:35], v[34:35], v[2:3] op_sel_hi:[1,0]
	v_pk_mul_f32 v[64:65], v[64:65], v[2:3] op_sel_hi:[1,0]
	v_pk_mul_f32 v[62:63], v[62:63], v[2:3] op_sel_hi:[1,0]
	v_pk_mul_f32 v[60:61], v[60:61], v[2:3] op_sel_hi:[1,0]
	v_pk_mul_f32 v[58:59], v[58:59], v[2:3] op_sel_hi:[1,0]
	v_pk_mul_f32 v[56:57], v[56:57], v[2:3] op_sel_hi:[1,0]
	v_pk_mul_f32 v[54:55], v[54:55], v[2:3] op_sel_hi:[1,0]
	v_pk_mul_f32 v[52:53], v[52:53], v[2:3] op_sel_hi:[1,0]
	v_pk_mul_f32 v[50:51], v[50:51], v[2:3] op_sel_hi:[1,0]
	v_mul_f32_e32 v161, v161, v2
.LBB0_593:
	v_fma_f32 v2, v33, s5, -v162
	v_exp_f32_e32 v33, v2
	v_fma_f32 v2, v32, s5, -v162
	v_exp_f32_e32 v32, v2
	v_fma_f32 v2, v31, s5, -v162
	v_exp_f32_e32 v31, v2
	v_fma_f32 v2, v30, s5, -v162
	v_exp_f32_e32 v30, v2
	v_fma_f32 v2, v29, s5, -v162
	v_exp_f32_e32 v29, v2
	v_fma_f32 v2, v28, s5, -v162
	v_exp_f32_e32 v28, v2
	v_fma_f32 v2, v27, s5, -v162
	v_exp_f32_e32 v27, v2
	v_fma_f32 v2, v26, s5, -v162
	v_exp_f32_e32 v26, v2
	v_fma_f32 v2, v25, s5, -v162
	v_exp_f32_e32 v25, v2
	v_fma_f32 v2, v24, s5, -v162
	v_fma_f32 v18, v18, s5, -v162
	v_exp_f32_e32 v24, v2
	v_fma_f32 v2, v23, s5, -v162
	v_fma_f32 v17, v19, s5, -v162
	v_exp_f32_e32 v18, v18
	v_exp_f32_e32 v23, v2
	v_fma_f32 v2, v22, s5, -v162
	v_fma_f32 v16, v20, s5, -v162
	v_exp_f32_e32 v19, v17
	v_exp_f32_e32 v22, v2
	v_fma_f32 v2, v21, s5, -v162
	v_exp_f32_e32 v20, v16
	v_exp_f32_e32 v21, v2
	v_add_f32_e32 v2, 0, v18
	v_add_f32_e32 v2, v19, v2
	v_add_f32_e32 v2, v20, v2
	v_add_f32_e32 v2, v21, v2
	v_add_f32_e32 v2, v22, v2
	v_add_f32_e32 v2, v23, v2
	v_add_f32_e32 v2, v24, v2
	v_add_f32_e32 v2, v25, v2
	v_add_f32_e32 v2, v26, v2
	v_add_f32_e32 v2, v27, v2
	v_add_f32_e32 v2, v28, v2
	v_add_f32_e32 v2, v29, v2
	v_add_f32_e32 v2, v30, v2
	v_add_f32_e32 v2, v31, v2
	v_add_f32_e32 v2, v32, v2
	v_add_f32_e32 v2, v33, v2
	v_cvt_pk_bf16_f32 v70, v18, v19
	v_cvt_pk_bf16_f32 v71, v20, v21
	v_cvt_pk_bf16_f32 v72, v22, v23
	v_cvt_pk_bf16_f32 v73, v24, v25
	v_cvt_pk_bf16_f32 v74, v26, v27
	v_cvt_pk_bf16_f32 v75, v28, v29
	v_cvt_pk_bf16_f32 v76, v30, v31
	v_cvt_pk_bf16_f32 v77, v32, v33
	s_waitcnt lgkmcnt(0)
	v_mfma_f32_32x32x16_bf16 v[34:49], v[98:101], v[70:73], v[34:49]
	v_add_f32_e32 v161, v161, v2
	v_mfma_f32_32x32x16_bf16 v[50:65], v[110:113], v[70:73], v[50:65]
	v_mfma_f32_32x32x16_bf16 v[34:49], v[102:105], v[74:77], v[34:49]
	v_mfma_f32_32x32x16_bf16 v[50:65], v[106:109], v[74:77], v[50:65]

.LBB0_596:
	v_add_u32_e32 v2, v151, v141
	s_waitcnt lgkmcnt(0)
	v_add_u32_e32 v4, v151, v142
	ds_read_b128 v[12:15], v2 offset:8192
	ds_read_b128 v[8:11], v4 offset:8192
	v_add_u32_e32 v2, v151, v143
	v_add_u32_e32 v4, v151, v144
	ds_read_b128 v[66:69], v2 offset:8192
	ds_read_b128 v[4:7], v4 offset:8192
	s_andn2_b64 vcc, exec, s[86:87]
	s_cbranch_vccnz .LBB0_600
	s_nop 0
	v_max_f32_e32 v2, v19, v19
	v_max_f32_e32 v16, v18, v18
	v_max_f32_e32 v2, v16, v2
	v_max3_f32 v2, v2, v20, v21
	v_max3_f32 v2, v2, v22, v23
	v_mbcnt_hi_u32_b32 v16, -1, v1
	v_max3_f32 v2, v2, v24, v25
	v_and_b32_e32 v70, 64, v16
	v_max3_f32 v2, v2, v26, v27
	v_xor_b32_e32 v17, 32, v16
	v_add_u32_e32 v70, 64, v70
	v_max3_f32 v2, v2, v28, v29
	v_cmp_lt_i32_e32 vcc, v17, v70
	v_max3_f32 v2, v2, v30, v31
	v_max3_f32 v2, v2, v32, v33
	v_cndmask_b32_e32 v16, v16, v17, vcc
	v_lshlrev_b32_e32 v16, 2, v16
	v_mov_b32_e32 v16, v2
	s_nop 1
	v_permlane32_swap_b32_e32 v16, v2
	s_nop 0
	v_max_f32_e32 v16, v16, v16
	v_max_f32_e32 v2, v2, v16
	v_mul_f32_e32 v2, 0x3fb8aa3b, v2
	v_add_f32_e32 v16, 0x41380000, v162
	v_cmp_gt_f32_e32 vcc, v2, v16
	s_cbranch_vccz .LBB0_599
	v_max_f32_e32 v2, v2, v2
	v_max_f32_e32 v16, v162, v162
	v_max_f32_e32 v16, v16, v2
	v_sub_f32_e32 v2, v162, v16
	v_exp_f32_e32 v2, v2
	v_mov_b32_e32 v162, v16
	v_pk_mul_f32 v[48:49], v[48:49], v[2:3] op_sel_hi:[1,0]
	v_pk_mul_f32 v[46:47], v[46:47], v[2:3] op_sel_hi:[1,0]
	v_pk_mul_f32 v[44:45], v[44:45], v[2:3] op_sel_hi:[1,0]
	v_pk_mul_f32 v[42:43], v[42:43], v[2:3] op_sel_hi:[1,0]
	v_pk_mul_f32 v[40:41], v[40:41], v[2:3] op_sel_hi:[1,0]
	v_pk_mul_f32 v[38:39], v[38:39], v[2:3] op_sel_hi:[1,0]
	v_pk_mul_f32 v[36:37], v[36:37], v[2:3] op_sel_hi:[1,0]
	v_pk_mul_f32 v[34:35], v[34:35], v[2:3] op_sel_hi:[1,0]
	v_pk_mul_f32 v[64:65], v[64:65], v[2:3] op_sel_hi:[1,0]
	v_pk_mul_f32 v[62:63], v[62:63], v[2:3] op_sel_hi:[1,0]
	v_pk_mul_f32 v[60:61], v[60:61], v[2:3] op_sel_hi:[1,0]
	v_pk_mul_f32 v[58:59], v[58:59], v[2:3] op_sel_hi:[1,0]
	v_pk_mul_f32 v[56:57], v[56:57], v[2:3] op_sel_hi:[1,0]
	v_pk_mul_f32 v[54:55], v[54:55], v[2:3] op_sel_hi:[1,0]
	v_pk_mul_f32 v[52:53], v[52:53], v[2:3] op_sel_hi:[1,0]
	v_pk_mul_f32 v[50:51], v[50:51], v[2:3] op_sel_hi:[1,0]
	v_mul_f32_e32 v161, v161, v2

.LBB0_602:
	v_add_u32_e32 v2, v152, v141
	s_waitcnt lgkmcnt(0)
	v_add_u32_e32 v4, v152, v142
	ds_read_b128 v[12:15], v2 offset:8192
	ds_read_b128 v[8:11], v4 offset:8192
	v_add_u32_e32 v2, v152, v143
	v_add_u32_e32 v4, v152, v144
	ds_read_b128 v[66:69], v2 offset:8192
	ds_read_b128 v[4:7], v4 offset:8192
	s_andn2_b64 vcc, exec, s[86:87]
	s_cbranch_vccnz .LBB0_606
	s_nop 0
	v_max_f32_e32 v2, v19, v19
	v_max_f32_e32 v16, v18, v18
	v_max_f32_e32 v2, v16, v2
	v_max3_f32 v2, v2, v20, v21
	v_max3_f32 v2, v2, v22, v23
	v_mbcnt_hi_u32_b32 v16, -1, v1
	v_max3_f32 v2, v2, v24, v25
	v_and_b32_e32 v70, 64, v16
	v_max3_f32 v2, v2, v26, v27
	v_xor_b32_e32 v17, 32, v16
	v_add_u32_e32 v70, 64, v70
	v_max3_f32 v2, v2, v28, v29
	v_cmp_lt_i32_e32 vcc, v17, v70
	v_max3_f32 v2, v2, v30, v31
	v_max3_f32 v2, v2, v32, v33
	v_cndmask_b32_e32 v16, v16, v17, vcc
	v_lshlrev_b32_e32 v16, 2, v16
	v_mov_b32_e32 v16, v2
	s_nop 1
	v_permlane32_swap_b32_e32 v16, v2
	s_nop 0
	v_max_f32_e32 v16, v16, v16
	v_max_f32_e32 v2, v2, v16
	v_mul_f32_e32 v2, 0x3fb8aa3b, v2
	v_add_f32_e32 v16, 0x41380000, v162
	v_cmp_gt_f32_e32 vcc, v2, v16
	s_cbranch_vccz .LBB0_605
	v_max_f32_e32 v2, v2, v2
	v_max_f32_e32 v16, v162, v162
	v_max_f32_e32 v16, v16, v2
	v_sub_f32_e32 v2, v162, v16
	v_exp_f32_e32 v2, v2
	v_mov_b32_e32 v162, v16
	v_pk_mul_f32 v[48:49], v[48:49], v[2:3] op_sel_hi:[1,0]
	v_pk_mul_f32 v[46:47], v[46:47], v[2:3] op_sel_hi:[1,0]
	v_pk_mul_f32 v[44:45], v[44:45], v[2:3] op_sel_hi:[1,0]
	v_pk_mul_f32 v[42:43], v[42:43], v[2:3] op_sel_hi:[1,0]
	v_pk_mul_f32 v[40:41], v[40:41], v[2:3] op_sel_hi:[1,0]
	v_pk_mul_f32 v[38:39], v[38:39], v[2:3] op_sel_hi:[1,0]
	v_pk_mul_f32 v[36:37], v[36:37], v[2:3] op_sel_hi:[1,0]
	v_pk_mul_f32 v[34:35], v[34:35], v[2:3] op_sel_hi:[1,0]
	v_pk_mul_f32 v[64:65], v[64:65], v[2:3] op_sel_hi:[1,0]
	v_pk_mul_f32 v[62:63], v[62:63], v[2:3] op_sel_hi:[1,0]
	v_pk_mul_f32 v[60:61], v[60:61], v[2:3] op_sel_hi:[1,0]
	v_pk_mul_f32 v[58:59], v[58:59], v[2:3] op_sel_hi:[1,0]
	v_pk_mul_f32 v[56:57], v[56:57], v[2:3] op_sel_hi:[1,0]
	v_pk_mul_f32 v[54:55], v[54:55], v[2:3] op_sel_hi:[1,0]
	v_pk_mul_f32 v[52:53], v[52:53], v[2:3] op_sel_hi:[1,0]
	v_pk_mul_f32 v[50:51], v[50:51], v[2:3] op_sel_hi:[1,0]
	v_mul_f32_e32 v161, v161, v2

.LBB0_712:
	v_add_u32_e32 v2, v170, v165
	v_add_u32_e32 v4, v170, v166
	ds_read_b128 v[122:125], v2 offset:8192
	ds_read_b128 v[118:121], v4 offset:8192
	v_add_u32_e32 v2, v170, v163
	v_add_u32_e32 v4, v170, v164
	ds_read_b128 v[126:129], v2 offset:8192
	ds_read_b128 v[114:117], v4 offset:8192
	s_andn2_b64 vcc, exec, s[4:5]
	s_cbranch_vccnz .LBB0_714
	s_nop 0
	v_max_f32_e32 v2, v19, v19
	v_max_f32_e32 v4, v18, v18
	v_max_f32_e32 v2, v4, v2
	v_max3_f32 v2, v2, v20, v21
	v_max3_f32 v2, v2, v22, v23
	v_max3_f32 v2, v2, v24, v25
	v_and_b32_e32 v5, 64, v160
	v_max3_f32 v2, v2, v26, v27
	v_xor_b32_e32 v4, 32, v160
	v_add_u32_e32 v5, 64, v5
	v_max3_f32 v2, v2, v28, v29
	v_cmp_lt_i32_e32 vcc, v4, v5
	v_max3_f32 v2, v2, v30, v31
	v_max3_f32 v2, v2, v32, v33
	v_cndmask_b32_e32 v4, v160, v4, vcc
	v_lshlrev_b32_e32 v4, 2, v4
	v_mov_b32_e32 v4, v2
	s_nop 1
	v_permlane32_swap_b32_e32 v4, v2
	s_nop 0
	s_mov_b32 s4, 0xf149f2ca
	v_max_f32_e32 v4, v4, v4
	v_max_f32_e32 v2, v2, v4
	v_mul_f32_e32 v2, 0x3fb8aa3b, v2
	v_max_f32_e32 v4, 0xf149f2ca, v2
	v_sub_f32_e32 v5, 0xf149f2ca, v4
	v_exp_f32_e32 v5, v5
	v_cmp_lt_f32_e32 vcc, s4, v2
	s_cmp_eq_u64 vcc, 0
	s_cselect_b64 vcc, -1, 0
	v_cndmask_b32_e32 v174, v4, v173, vcc
	v_mul_f32_e32 v2, 0, v5
	v_fma_f32 v6, v30, s23, -v174
	v_cndmask_b32_e64 v66, v2, 0, vcc
	v_fma_f32 v2, v33, s23, -v174
	v_fma_f32 v5, v31, s23, -v174
	v_exp_f32_e32 v6, v6
	v_exp_f32_e32 v2, v2
	v_fma_f32 v4, v32, s23, -v174
	v_exp_f32_e32 v5, v5
	v_exp_f32_e32 v4, v4
	v_cndmask_b32_e64 v30, 0, v6, s[68:69]
	v_fma_f32 v6, v26, s23, -v174
	v_cndmask_b32_e64 v33, 0, v2, s[62:63]
	v_cndmask_b32_e64 v31, 0, v5, s[66:67]
	v_fma_f32 v2, v29, s23, -v174
	v_fma_f32 v5, v27, s23, -v174
	v_exp_f32_e32 v6, v6
	v_cndmask_b32_e64 v32, 0, v4, s[64:65]
	v_exp_f32_e32 v2, v2
	v_fma_f32 v4, v28, s23, -v174
	v_exp_f32_e32 v5, v5
	v_exp_f32_e32 v4, v4
	v_cndmask_b32_e64 v26, 0, v6, s[60:61]
	v_fma_f32 v6, v22, s23, -v174
	v_cndmask_b32_e64 v29, 0, v2, s[54:55]
	v_cndmask_b32_e64 v27, 0, v5, s[58:59]
	v_fma_f32 v2, v25, s23, -v174
	v_fma_f32 v5, v23, s23, -v174
	v_exp_f32_e32 v6, v6
	v_cndmask_b32_e64 v28, 0, v4, s[56:57]
	v_exp_f32_e32 v2, v2
	v_fma_f32 v4, v24, s23, -v174
	v_exp_f32_e32 v5, v5
	v_exp_f32_e32 v4, v4
	v_cndmask_b32_e64 v22, 0, v6, s[52:53]
	v_fma_f32 v6, v18, s23, -v174
	v_cndmask_b32_e64 v25, 0, v2, s[46:47]
	v_cndmask_b32_e64 v23, 0, v5, s[50:51]
	v_fma_f32 v2, v21, s23, -v174
	v_fma_f32 v5, v19, s23, -v174
	v_exp_f32_e32 v6, v6
	v_cndmask_b32_e64 v24, 0, v4, s[48:49]
	v_exp_f32_e32 v2, v2
	v_fma_f32 v4, v20, s23, -v174
	v_exp_f32_e32 v5, v5
	v_exp_f32_e32 v4, v4
	v_cndmask_b32_e64 v18, 0, v6, s[44:45]
	v_cndmask_b32_e64 v21, 0, v2, s[38:39]
	v_cndmask_b32_e64 v19, 0, v5, s[42:43]
	v_add_f32_e32 v2, 0, v18
	v_cndmask_b32_e64 v20, 0, v4, s[40:41]
	v_add_f32_e32 v2, v19, v2
	v_add_f32_e32 v2, v20, v2
	v_add_f32_e32 v2, v21, v2
	v_add_f32_e32 v2, v22, v2
	v_add_f32_e32 v2, v23, v2
	v_add_f32_e32 v2, v24, v2
	v_add_f32_e32 v2, v25, v2
	v_add_f32_e32 v2, v26, v2
	v_add_f32_e32 v2, v27, v2
	v_add_f32_e32 v2, v28, v2
	v_add_f32_e32 v2, v29, v2
	v_add_f32_e32 v2, v30, v2
	v_add_f32_e32 v2, v31, v2
	v_add_f32_e32 v2, v32, v2
	v_mov_b32_e32 v67, v66
	v_mov_b32_e32 v68, v66
	v_mov_b32_e32 v69, v66
	v_mov_b32_e32 v70, v66
	v_mov_b32_e32 v71, v66
	v_mov_b32_e32 v72, v66
	v_mov_b32_e32 v73, v66
	v_mov_b32_e32 v74, v66
	v_mov_b32_e32 v75, v66
	v_mov_b32_e32 v76, v66
	v_mov_b32_e32 v77, v66
	v_mov_b32_e32 v78, v66
	v_mov_b32_e32 v79, v66
	v_mov_b32_e32 v80, v66
	v_mov_b32_e32 v81, v66
	v_add_f32_e32 v2, v33, v2
	v_cvt_pk_bf16_f32 v4, v18, v19
	v_cvt_pk_bf16_f32 v5, v20, v21
	v_cvt_pk_bf16_f32 v6, v22, v23
	v_cvt_pk_bf16_f32 v7, v24, v25
	v_cvt_pk_bf16_f32 v8, v26, v27
	v_cvt_pk_bf16_f32 v9, v28, v29
	v_cvt_pk_bf16_f32 v10, v30, v31
	v_cvt_pk_bf16_f32 v11, v32, v33
	v_mov_b64_e32 v[50:51], v[66:67]
	v_mov_b64_e32 v[52:53], v[68:69]
	v_mov_b64_e32 v[54:55], v[70:71]
	v_mov_b64_e32 v[56:57], v[72:73]
	v_mov_b64_e32 v[58:59], v[74:75]
	v_mov_b64_e32 v[60:61], v[76:77]
	v_mov_b64_e32 v[62:63], v[78:79]
	v_mov_b64_e32 v[64:65], v[80:81]
	s_waitcnt lgkmcnt(0)
	v_mfma_f32_32x32x16_bf16 v[34:49], v[98:101], v[4:7], v[66:81]
	v_add_f32_e32 v153, v66, v2
	v_mfma_f32_32x32x16_bf16 v[50:65], v[110:113], v[4:7], v[50:65]
	v_mfma_f32_32x32x16_bf16 v[34:49], v[102:105], v[8:11], v[34:49]
	v_mfma_f32_32x32x16_bf16 v[50:65], v[106:109], v[8:11], v[50:65]
	s_cmp_ge_i32 s13, s25
	s_cselect_b64 s[4:5], -1, 0
	s_cmp_lt_i32 s13, s25
	s_cbranch_scc0 .LBB0_715
	s_branch .LBB0_716

.LBB0_716:
	v_add_u32_e32 v2, v169, v165
	v_add_u32_e32 v4, v169, v166
	ds_read_b128 v[12:15], v2 offset:8192
	ds_read_b128 v[8:11], v4 offset:8192
	v_add_u32_e32 v2, v169, v163
	v_add_u32_e32 v4, v169, v164
	ds_read_b128 v[66:69], v2 offset:8192
	ds_read_b128 v[4:7], v4 offset:8192
	s_andn2_b64 vcc, exec, s[4:5]
	s_cbranch_vccnz .LBB0_720
	s_nop 1
	v_max_f32_e32 v2, v19, v19
	v_max_f32_e32 v16, v18, v18
	v_max_f32_e32 v2, v16, v2
	v_max3_f32 v2, v2, v20, v21
	v_max3_f32 v2, v2, v22, v23
	v_mbcnt_hi_u32_b32 v16, -1, v1
	v_max3_f32 v2, v2, v24, v25
	v_and_b32_e32 v70, 64, v16
	v_max3_f32 v2, v2, v26, v27
	v_xor_b32_e32 v17, 32, v16
	v_add_u32_e32 v70, 64, v70
	v_max3_f32 v2, v2, v28, v29
	v_cmp_lt_i32_e32 vcc, v17, v70
	v_max3_f32 v2, v2, v30, v31
	v_max3_f32 v2, v2, v32, v33
	v_cndmask_b32_e32 v16, v16, v17, vcc
	v_lshlrev_b32_e32 v16, 2, v16
	v_mov_b32_e32 v16, v2
	s_nop 1
	v_permlane32_swap_b32_e32 v16, v2
	s_nop 0
	v_max_f32_e32 v16, v16, v16
	v_max_f32_e32 v2, v2, v16
	v_mul_f32_e32 v2, 0x3fb8aa3b, v2
	v_add_f32_e32 v16, 0x41380000, v174
	v_cmp_gt_f32_e32 vcc, v2, v16
	s_cbranch_vccz .LBB0_719
	v_max_f32_e32 v2, v2, v2
	v_max_f32_e32 v16, v174, v174
	v_max_f32_e32 v16, v16, v2
	v_sub_f32_e32 v2, v174, v16
	v_exp_f32_e32 v2, v2
	v_mov_b32_e32 v174, v16
	v_pk_mul_f32 v[48:49], v[48:49], v[2:3] op_sel_hi:[1,0]
	v_pk_mul_f32 v[46:47], v[46:47], v[2:3] op_sel_hi:[1,0]
	v_pk_mul_f32 v[44:45], v[44:45], v[2:3] op_sel_hi:[1,0]
	v_pk_mul_f32 v[42:43], v[42:43], v[2:3] op_sel_hi:[1,0]
	v_pk_mul_f32 v[40:41], v[40:41], v[2:3] op_sel_hi:[1,0]
	v_pk_mul_f32 v[38:39], v[38:39], v[2:3] op_sel_hi:[1,0]
	v_pk_mul_f32 v[36:37], v[36:37], v[2:3] op_sel_hi:[1,0]
	v_pk_mul_f32 v[34:35], v[34:35], v[2:3] op_sel_hi:[1,0]
	v_pk_mul_f32 v[64:65], v[64:65], v[2:3] op_sel_hi:[1,0]
	v_pk_mul_f32 v[62:63], v[62:63], v[2:3] op_sel_hi:[1,0]
	v_pk_mul_f32 v[60:61], v[60:61], v[2:3] op_sel_hi:[1,0]
	v_pk_mul_f32 v[58:59], v[58:59], v[2:3] op_sel_hi:[1,0]
	v_pk_mul_f32 v[56:57], v[56:57], v[2:3] op_sel_hi:[1,0]
	v_pk_mul_f32 v[54:55], v[54:55], v[2:3] op_sel_hi:[1,0]
	v_pk_mul_f32 v[52:53], v[52:53], v[2:3] op_sel_hi:[1,0]
	v_pk_mul_f32 v[50:51], v[50:51], v[2:3] op_sel_hi:[1,0]
	v_mul_f32_e32 v153, v153, v2
.LBB0_719:
	v_fma_f32 v2, v33, s23, -v174
	v_exp_f32_e32 v33, v2
	v_fma_f32 v2, v32, s23, -v174
	v_exp_f32_e32 v32, v2
	v_fma_f32 v2, v31, s23, -v174
	v_exp_f32_e32 v31, v2
	v_fma_f32 v2, v30, s23, -v174
	v_exp_f32_e32 v30, v2
	v_fma_f32 v2, v29, s23, -v174
	v_exp_f32_e32 v29, v2
	v_fma_f32 v2, v28, s23, -v174
	v_exp_f32_e32 v28, v2
	v_fma_f32 v2, v27, s23, -v174
	v_exp_f32_e32 v27, v2
	v_fma_f32 v2, v26, s23, -v174
	v_exp_f32_e32 v26, v2
	v_fma_f32 v2, v25, s23, -v174
	v_exp_f32_e32 v25, v2
	v_fma_f32 v2, v24, s23, -v174
	v_fma_f32 v18, v18, s23, -v174
	v_exp_f32_e32 v24, v2
	v_fma_f32 v2, v23, s23, -v174
	v_fma_f32 v17, v19, s23, -v174
	v_exp_f32_e32 v18, v18
	v_exp_f32_e32 v23, v2
	v_fma_f32 v2, v22, s23, -v174
	v_fma_f32 v16, v20, s23, -v174
	v_exp_f32_e32 v19, v17
	v_exp_f32_e32 v22, v2
	v_fma_f32 v2, v21, s23, -v174
	v_exp_f32_e32 v20, v16
	v_exp_f32_e32 v21, v2
	v_add_f32_e32 v2, 0, v18
	v_add_f32_e32 v2, v19, v2
	v_add_f32_e32 v2, v20, v2
	v_add_f32_e32 v2, v21, v2
	v_add_f32_e32 v2, v22, v2
	v_add_f32_e32 v2, v23, v2
	v_add_f32_e32 v2, v24, v2
	v_add_f32_e32 v2, v25, v2
	v_add_f32_e32 v2, v26, v2
	v_add_f32_e32 v2, v27, v2
	v_add_f32_e32 v2, v28, v2
	v_add_f32_e32 v2, v29, v2
	v_add_f32_e32 v2, v30, v2
	v_add_f32_e32 v2, v31, v2
	v_add_f32_e32 v2, v32, v2
	v_add_f32_e32 v2, v33, v2
	v_cvt_pk_bf16_f32 v70, v18, v19
	v_cvt_pk_bf16_f32 v71, v20, v21
	v_cvt_pk_bf16_f32 v72, v22, v23
	v_cvt_pk_bf16_f32 v73, v24, v25
	v_cvt_pk_bf16_f32 v74, v26, v27
	v_cvt_pk_bf16_f32 v75, v28, v29
	v_cvt_pk_bf16_f32 v76, v30, v31
	v_cvt_pk_bf16_f32 v77, v32, v33
	s_waitcnt lgkmcnt(0)
	v_mfma_f32_32x32x16_bf16 v[34:49], v[98:101], v[70:73], v[34:49]
	v_add_f32_e32 v153, v153, v2
	v_mfma_f32_32x32x16_bf16 v[50:65], v[110:113], v[70:73], v[50:65]
	v_mfma_f32_32x32x16_bf16 v[34:49], v[102:105], v[74:77], v[34:49]
	v_mfma_f32_32x32x16_bf16 v[50:65], v[106:109], v[74:77], v[50:65]

.LBB0_722:
	v_add_u32_e32 v2, v168, v165
	s_waitcnt lgkmcnt(0)
	v_add_u32_e32 v4, v168, v166
	ds_read_b128 v[12:15], v2 offset:8192
	ds_read_b128 v[8:11], v4 offset:8192
	v_add_u32_e32 v2, v168, v163
	v_add_u32_e32 v4, v168, v164
	ds_read_b128 v[66:69], v2 offset:8192
	ds_read_b128 v[4:7], v4 offset:8192
	s_andn2_b64 vcc, exec, s[4:5]
	s_cbranch_vccnz .LBB0_726
	s_nop 0
	v_max_f32_e32 v2, v19, v19
	v_max_f32_e32 v16, v18, v18
	v_max_f32_e32 v2, v16, v2
	v_max3_f32 v2, v2, v20, v21
	v_max3_f32 v2, v2, v22, v23
	v_mbcnt_hi_u32_b32 v16, -1, v1
	v_max3_f32 v2, v2, v24, v25
	v_and_b32_e32 v70, 64, v16
	v_max3_f32 v2, v2, v26, v27
	v_xor_b32_e32 v17, 32, v16
	v_add_u32_e32 v70, 64, v70
	v_max3_f32 v2, v2, v28, v29
	v_cmp_lt_i32_e32 vcc, v17, v70
	v_max3_f32 v2, v2, v30, v31
	v_max3_f32 v2, v2, v32, v33
	v_cndmask_b32_e32 v16, v16, v17, vcc
	v_lshlrev_b32_e32 v16, 2, v16
	v_mov_b32_e32 v16, v2
	s_nop 1
	v_permlane32_swap_b32_e32 v16, v2
	s_nop 0
	v_max_f32_e32 v16, v16, v16
	v_max_f32_e32 v2, v2, v16
	v_mul_f32_e32 v2, 0x3fb8aa3b, v2
	v_add_f32_e32 v16, 0x41380000, v174
	v_cmp_gt_f32_e32 vcc, v2, v16
	s_cbranch_vccz .LBB0_725
	v_max_f32_e32 v2, v2, v2
	v_max_f32_e32 v16, v174, v174
	v_max_f32_e32 v16, v16, v2
	v_sub_f32_e32 v2, v174, v16
	v_exp_f32_e32 v2, v2
	v_mov_b32_e32 v174, v16
	v_pk_mul_f32 v[48:49], v[48:49], v[2:3] op_sel_hi:[1,0]
	v_pk_mul_f32 v[46:47], v[46:47], v[2:3] op_sel_hi:[1,0]
	v_pk_mul_f32 v[44:45], v[44:45], v[2:3] op_sel_hi:[1,0]
	v_pk_mul_f32 v[42:43], v[42:43], v[2:3] op_sel_hi:[1,0]
	v_pk_mul_f32 v[40:41], v[40:41], v[2:3] op_sel_hi:[1,0]
	v_pk_mul_f32 v[38:39], v[38:39], v[2:3] op_sel_hi:[1,0]
	v_pk_mul_f32 v[36:37], v[36:37], v[2:3] op_sel_hi:[1,0]
	v_pk_mul_f32 v[34:35], v[34:35], v[2:3] op_sel_hi:[1,0]
	v_pk_mul_f32 v[64:65], v[64:65], v[2:3] op_sel_hi:[1,0]
	v_pk_mul_f32 v[62:63], v[62:63], v[2:3] op_sel_hi:[1,0]
	v_pk_mul_f32 v[60:61], v[60:61], v[2:3] op_sel_hi:[1,0]
	v_pk_mul_f32 v[58:59], v[58:59], v[2:3] op_sel_hi:[1,0]
	v_pk_mul_f32 v[56:57], v[56:57], v[2:3] op_sel_hi:[1,0]
	v_pk_mul_f32 v[54:55], v[54:55], v[2:3] op_sel_hi:[1,0]
	v_pk_mul_f32 v[52:53], v[52:53], v[2:3] op_sel_hi:[1,0]
	v_pk_mul_f32 v[50:51], v[50:51], v[2:3] op_sel_hi:[1,0]
	v_mul_f32_e32 v153, v153, v2

.LBB0_728:
	v_add_u32_e32 v2, v167, v165
	s_waitcnt lgkmcnt(0)
	v_add_u32_e32 v4, v167, v166
	ds_read_b128 v[12:15], v2 offset:8192
	ds_read_b128 v[8:11], v4 offset:8192
	v_add_u32_e32 v2, v167, v163
	v_add_u32_e32 v4, v167, v164
	ds_read_b128 v[66:69], v2 offset:8192
	ds_read_b128 v[4:7], v4 offset:8192
	s_andn2_b64 vcc, exec, s[4:5]
	s_cbranch_vccnz .LBB0_732
	s_nop 0
	v_max_f32_e32 v2, v19, v19
	v_max_f32_e32 v16, v18, v18
	v_max_f32_e32 v2, v16, v2
	v_max3_f32 v2, v2, v20, v21
	v_max3_f32 v2, v2, v22, v23
	v_mbcnt_hi_u32_b32 v16, -1, v1
	v_max3_f32 v2, v2, v24, v25
	v_and_b32_e32 v70, 64, v16
	v_max3_f32 v2, v2, v26, v27
	v_xor_b32_e32 v17, 32, v16
	v_add_u32_e32 v70, 64, v70
	v_max3_f32 v2, v2, v28, v29
	v_cmp_lt_i32_e32 vcc, v17, v70
	v_max3_f32 v2, v2, v30, v31
	v_max3_f32 v2, v2, v32, v33
	v_cndmask_b32_e32 v16, v16, v17, vcc
	v_lshlrev_b32_e32 v16, 2, v16
	v_mov_b32_e32 v16, v2
	s_nop 1
	v_permlane32_swap_b32_e32 v16, v2
	s_nop 0
	v_max_f32_e32 v16, v16, v16
	v_max_f32_e32 v2, v2, v16
	v_mul_f32_e32 v2, 0x3fb8aa3b, v2
	v_add_f32_e32 v16, 0x41380000, v174
	v_cmp_gt_f32_e32 vcc, v2, v16
	s_cbranch_vccz .LBB0_731
	v_max_f32_e32 v2, v2, v2
	v_max_f32_e32 v16, v174, v174
	v_max_f32_e32 v16, v16, v2
	v_sub_f32_e32 v2, v174, v16
	v_exp_f32_e32 v2, v2
	v_mov_b32_e32 v174, v16
	v_pk_mul_f32 v[48:49], v[48:49], v[2:3] op_sel_hi:[1,0]
	v_pk_mul_f32 v[46:47], v[46:47], v[2:3] op_sel_hi:[1,0]
	v_pk_mul_f32 v[44:45], v[44:45], v[2:3] op_sel_hi:[1,0]
	v_pk_mul_f32 v[42:43], v[42:43], v[2:3] op_sel_hi:[1,0]
	v_pk_mul_f32 v[40:41], v[40:41], v[2:3] op_sel_hi:[1,0]
	v_pk_mul_f32 v[38:39], v[38:39], v[2:3] op_sel_hi:[1,0]
	v_pk_mul_f32 v[36:37], v[36:37], v[2:3] op_sel_hi:[1,0]
	v_pk_mul_f32 v[34:35], v[34:35], v[2:3] op_sel_hi:[1,0]
	v_pk_mul_f32 v[64:65], v[64:65], v[2:3] op_sel_hi:[1,0]
	v_pk_mul_f32 v[62:63], v[62:63], v[2:3] op_sel_hi:[1,0]
	v_pk_mul_f32 v[60:61], v[60:61], v[2:3] op_sel_hi:[1,0]
	v_pk_mul_f32 v[58:59], v[58:59], v[2:3] op_sel_hi:[1,0]
	v_pk_mul_f32 v[56:57], v[56:57], v[2:3] op_sel_hi:[1,0]
	v_pk_mul_f32 v[54:55], v[54:55], v[2:3] op_sel_hi:[1,0]
	v_pk_mul_f32 v[52:53], v[52:53], v[2:3] op_sel_hi:[1,0]
	v_pk_mul_f32 v[50:51], v[50:51], v[2:3] op_sel_hi:[1,0]
	v_mul_f32_e32 v153, v153, v2

.LBB0_751:
	v_add_u32_e32 v2, v170, v165
	v_add_u32_e32 v4, v170, v166
	ds_read_b128 v[122:125], v2 offset:8192
	ds_read_b128 v[118:121], v4 offset:8192
	v_add_u32_e32 v2, v170, v163
	v_add_u32_e32 v4, v170, v164
	ds_read_b128 v[126:129], v2 offset:8192
	ds_read_b128 v[114:117], v4 offset:8192
	s_andn2_b64 vcc, exec, s[94:95]
	s_cbranch_vccnz .LBB0_753
	s_nop 0
	v_max_f32_e32 v2, v19, v19
	v_max_f32_e32 v4, v18, v18
	v_max_f32_e32 v2, v4, v2
	v_max3_f32 v2, v2, v20, v21
	v_max3_f32 v2, v2, v22, v23
	v_mbcnt_hi_u32_b32 v4, -1, v1
	v_max3_f32 v2, v2, v24, v25
	v_and_b32_e32 v6, 64, v4
	v_max3_f32 v2, v2, v26, v27
	v_xor_b32_e32 v5, 32, v4
	v_add_u32_e32 v6, 64, v6
	v_max3_f32 v2, v2, v28, v29
	v_cmp_lt_i32_e32 vcc, v5, v6
	v_max3_f32 v2, v2, v30, v31
	v_max3_f32 v2, v2, v32, v33
	v_cndmask_b32_e32 v4, v4, v5, vcc
	v_lshlrev_b32_e32 v4, 2, v4
	v_mov_b32_e32 v4, v2
	s_nop 1
	v_permlane32_swap_b32_e32 v4, v2
	s_nop 0
	s_mov_b32 s5, 0xf149f2ca
	v_max_f32_e32 v4, v4, v4
	v_max_f32_e32 v2, v2, v4
	v_mul_f32_e32 v2, 0x3fb8aa3b, v2
	v_max_f32_e32 v4, 0xf149f2ca, v2
	v_sub_f32_e32 v5, 0xf149f2ca, v4
	v_exp_f32_e32 v5, v5
	v_cmp_lt_f32_e32 vcc, s5, v2
	s_cmp_eq_u64 vcc, 0
	s_cselect_b64 vcc, -1, 0
	v_cndmask_b32_e32 v153, v4, v173, vcc
	v_mul_f32_e32 v2, 0, v5
	v_fma_f32 v6, v30, s23, -v153
	v_cndmask_b32_e64 v66, v2, 0, vcc
	v_fma_f32 v2, v33, s23, -v153
	v_fma_f32 v5, v31, s23, -v153
	v_exp_f32_e32 v6, v6
	v_exp_f32_e32 v2, v2
	v_fma_f32 v4, v32, s23, -v153
	v_exp_f32_e32 v5, v5
	v_exp_f32_e32 v4, v4
	v_cndmask_b32_e64 v30, 0, v6, s[68:69]
	v_fma_f32 v6, v26, s23, -v153
	v_cndmask_b32_e64 v33, 0, v2, s[62:63]
	v_cndmask_b32_e64 v31, 0, v5, s[66:67]
	v_fma_f32 v2, v29, s23, -v153
	v_fma_f32 v5, v27, s23, -v153
	v_exp_f32_e32 v6, v6
	v_cndmask_b32_e64 v32, 0, v4, s[64:65]
	v_exp_f32_e32 v2, v2
	v_fma_f32 v4, v28, s23, -v153
	v_exp_f32_e32 v5, v5
	v_exp_f32_e32 v4, v4
	v_cndmask_b32_e64 v26, 0, v6, s[60:61]
	v_fma_f32 v6, v22, s23, -v153
	v_cndmask_b32_e64 v29, 0, v2, s[54:55]
	v_cndmask_b32_e64 v27, 0, v5, s[58:59]
	v_fma_f32 v2, v25, s23, -v153
	v_fma_f32 v5, v23, s23, -v153
	v_exp_f32_e32 v6, v6
	v_cndmask_b32_e64 v28, 0, v4, s[56:57]
	v_exp_f32_e32 v2, v2
	v_fma_f32 v4, v24, s23, -v153
	v_exp_f32_e32 v5, v5
	v_exp_f32_e32 v4, v4
	v_cndmask_b32_e64 v22, 0, v6, s[52:53]
	v_fma_f32 v6, v18, s23, -v153
	v_cndmask_b32_e64 v25, 0, v2, s[46:47]
	v_cndmask_b32_e64 v23, 0, v5, s[50:51]
	v_fma_f32 v2, v21, s23, -v153
	v_fma_f32 v5, v19, s23, -v153
	v_exp_f32_e32 v6, v6
	v_cndmask_b32_e64 v24, 0, v4, s[48:49]
	v_exp_f32_e32 v2, v2
	v_fma_f32 v4, v20, s23, -v153
	v_exp_f32_e32 v5, v5
	v_exp_f32_e32 v4, v4
	v_cndmask_b32_e64 v18, 0, v6, s[44:45]
	v_cndmask_b32_e64 v21, 0, v2, s[38:39]
	v_cndmask_b32_e64 v19, 0, v5, s[42:43]
	v_add_f32_e32 v2, 0, v18
	v_cndmask_b32_e64 v20, 0, v4, s[40:41]
	v_add_f32_e32 v2, v19, v2
	v_add_f32_e32 v2, v20, v2
	v_add_f32_e32 v2, v21, v2
	v_add_f32_e32 v2, v22, v2
	v_add_f32_e32 v2, v23, v2
	v_add_f32_e32 v2, v24, v2
	v_add_f32_e32 v2, v25, v2
	v_add_f32_e32 v2, v26, v2
	v_add_f32_e32 v2, v27, v2
	v_add_f32_e32 v2, v28, v2
	v_add_f32_e32 v2, v29, v2
	v_add_f32_e32 v2, v30, v2
	v_add_f32_e32 v2, v31, v2
	v_add_f32_e32 v2, v32, v2
	v_mov_b32_e32 v67, v66
	v_mov_b32_e32 v68, v66
	v_mov_b32_e32 v69, v66
	v_mov_b32_e32 v70, v66
	v_mov_b32_e32 v71, v66
	v_mov_b32_e32 v72, v66
	v_mov_b32_e32 v73, v66
	v_mov_b32_e32 v74, v66
	v_mov_b32_e32 v75, v66
	v_mov_b32_e32 v76, v66
	v_mov_b32_e32 v77, v66
	v_mov_b32_e32 v78, v66
	v_mov_b32_e32 v79, v66
	v_mov_b32_e32 v80, v66
	v_mov_b32_e32 v81, v66
	v_add_f32_e32 v2, v33, v2
	v_cvt_pk_bf16_f32 v4, v18, v19
	v_cvt_pk_bf16_f32 v5, v20, v21
	v_cvt_pk_bf16_f32 v6, v22, v23
	v_cvt_pk_bf16_f32 v7, v24, v25
	v_cvt_pk_bf16_f32 v8, v26, v27
	v_cvt_pk_bf16_f32 v9, v28, v29
	v_cvt_pk_bf16_f32 v10, v30, v31
	v_cvt_pk_bf16_f32 v11, v32, v33
	v_mov_b64_e32 v[50:51], v[66:67]
	v_mov_b64_e32 v[52:53], v[68:69]
	v_mov_b64_e32 v[54:55], v[70:71]
	v_mov_b64_e32 v[56:57], v[72:73]
	v_mov_b64_e32 v[58:59], v[74:75]
	v_mov_b64_e32 v[60:61], v[76:77]
	v_mov_b64_e32 v[62:63], v[78:79]
	v_mov_b64_e32 v[64:65], v[80:81]
	s_waitcnt lgkmcnt(0)
	v_mfma_f32_32x32x16_bf16 v[34:49], v[98:101], v[4:7], v[66:81]
	v_add_f32_e32 v152, v66, v2
	v_mfma_f32_32x32x16_bf16 v[50:65], v[110:113], v[4:7], v[50:65]
	v_mfma_f32_32x32x16_bf16 v[34:49], v[102:105], v[8:11], v[34:49]
	v_mfma_f32_32x32x16_bf16 v[50:65], v[106:109], v[8:11], v[50:65]
	v_cndmask_b32_e64 v2, 0, 1, s[90:91]
	v_cmp_ne_u32_e64 s[70:71], 1, v2
	s_andn2_b64 vcc, exec, s[90:91]
	s_cbranch_vccz .LBB0_754
	s_branch .LBB0_755

.LBB0_755:
	v_add_u32_e32 v2, v169, v165
	v_add_u32_e32 v4, v169, v166
	ds_read_b128 v[12:15], v2 offset:8192
	ds_read_b128 v[8:11], v4 offset:8192
	v_add_u32_e32 v2, v169, v163
	v_add_u32_e32 v4, v169, v164
	ds_read_b128 v[66:69], v2 offset:8192
	ds_read_b128 v[4:7], v4 offset:8192
	s_and_b64 vcc, exec, s[70:71]
	s_cbranch_vccnz .LBB0_759
	s_nop 1
	v_max_f32_e32 v2, v19, v19
	v_max_f32_e32 v16, v18, v18
	v_max_f32_e32 v2, v16, v2
	v_max3_f32 v2, v2, v20, v21
	v_max3_f32 v2, v2, v22, v23
	v_mbcnt_hi_u32_b32 v16, -1, v1
	v_max3_f32 v2, v2, v24, v25
	v_and_b32_e32 v70, 64, v16
	v_max3_f32 v2, v2, v26, v27
	v_xor_b32_e32 v17, 32, v16
	v_add_u32_e32 v70, 64, v70
	v_max3_f32 v2, v2, v28, v29
	v_cmp_lt_i32_e32 vcc, v17, v70
	v_max3_f32 v2, v2, v30, v31
	v_max3_f32 v2, v2, v32, v33
	v_cndmask_b32_e32 v16, v16, v17, vcc
	v_lshlrev_b32_e32 v16, 2, v16
	v_mov_b32_e32 v16, v2
	s_nop 1
	v_permlane32_swap_b32_e32 v16, v2
	s_nop 0
	v_max_f32_e32 v16, v16, v16
	v_max_f32_e32 v2, v2, v16
	v_mul_f32_e32 v2, 0x3fb8aa3b, v2
	v_add_f32_e32 v16, 0x41380000, v153
	v_cmp_gt_f32_e32 vcc, v2, v16
	s_cbranch_vccz .LBB0_758
	v_max_f32_e32 v2, v2, v2
	v_max_f32_e32 v16, v153, v153
	v_max_f32_e32 v16, v16, v2
	v_sub_f32_e32 v2, v153, v16
	v_exp_f32_e32 v2, v2
	v_mov_b32_e32 v153, v16
	v_pk_mul_f32 v[48:49], v[48:49], v[2:3] op_sel_hi:[1,0]
	v_pk_mul_f32 v[46:47], v[46:47], v[2:3] op_sel_hi:[1,0]
	v_pk_mul_f32 v[44:45], v[44:45], v[2:3] op_sel_hi:[1,0]
	v_pk_mul_f32 v[42:43], v[42:43], v[2:3] op_sel_hi:[1,0]
	v_pk_mul_f32 v[40:41], v[40:41], v[2:3] op_sel_hi:[1,0]
	v_pk_mul_f32 v[38:39], v[38:39], v[2:3] op_sel_hi:[1,0]
	v_pk_mul_f32 v[36:37], v[36:37], v[2:3] op_sel_hi:[1,0]
	v_pk_mul_f32 v[34:35], v[34:35], v[2:3] op_sel_hi:[1,0]
	v_pk_mul_f32 v[64:65], v[64:65], v[2:3] op_sel_hi:[1,0]
	v_pk_mul_f32 v[62:63], v[62:63], v[2:3] op_sel_hi:[1,0]
	v_pk_mul_f32 v[60:61], v[60:61], v[2:3] op_sel_hi:[1,0]
	v_pk_mul_f32 v[58:59], v[58:59], v[2:3] op_sel_hi:[1,0]
	v_pk_mul_f32 v[56:57], v[56:57], v[2:3] op_sel_hi:[1,0]
	v_pk_mul_f32 v[54:55], v[54:55], v[2:3] op_sel_hi:[1,0]
	v_pk_mul_f32 v[52:53], v[52:53], v[2:3] op_sel_hi:[1,0]
	v_pk_mul_f32 v[50:51], v[50:51], v[2:3] op_sel_hi:[1,0]
	v_mul_f32_e32 v152, v152, v2
.LBB0_758:
	v_fma_f32 v2, v33, s23, -v153
	v_exp_f32_e32 v33, v2
	v_fma_f32 v2, v32, s23, -v153
	v_exp_f32_e32 v32, v2
	v_fma_f32 v2, v31, s23, -v153
	v_exp_f32_e32 v31, v2
	v_fma_f32 v2, v30, s23, -v153
	v_exp_f32_e32 v30, v2
	v_fma_f32 v2, v29, s23, -v153
	v_exp_f32_e32 v29, v2
	v_fma_f32 v2, v28, s23, -v153
	v_exp_f32_e32 v28, v2
	v_fma_f32 v2, v27, s23, -v153
	v_exp_f32_e32 v27, v2
	v_fma_f32 v2, v26, s23, -v153
	v_exp_f32_e32 v26, v2
	v_fma_f32 v2, v25, s23, -v153
	v_exp_f32_e32 v25, v2
	v_fma_f32 v2, v24, s23, -v153
	v_fma_f32 v18, v18, s23, -v153
	v_exp_f32_e32 v24, v2
	v_fma_f32 v2, v23, s23, -v153
	v_fma_f32 v17, v19, s23, -v153
	v_exp_f32_e32 v18, v18
	v_exp_f32_e32 v23, v2
	v_fma_f32 v2, v22, s23, -v153
	v_fma_f32 v16, v20, s23, -v153
	v_exp_f32_e32 v19, v17
	v_exp_f32_e32 v22, v2
	v_fma_f32 v2, v21, s23, -v153
	v_exp_f32_e32 v20, v16
	v_exp_f32_e32 v21, v2
	v_add_f32_e32 v2, 0, v18
	v_add_f32_e32 v2, v19, v2
	v_add_f32_e32 v2, v20, v2
	v_add_f32_e32 v2, v21, v2
	v_add_f32_e32 v2, v22, v2
	v_add_f32_e32 v2, v23, v2
	v_add_f32_e32 v2, v24, v2
	v_add_f32_e32 v2, v25, v2
	v_add_f32_e32 v2, v26, v2
	v_add_f32_e32 v2, v27, v2
	v_add_f32_e32 v2, v28, v2
	v_add_f32_e32 v2, v29, v2
	v_add_f32_e32 v2, v30, v2
	v_add_f32_e32 v2, v31, v2
	v_add_f32_e32 v2, v32, v2
	v_add_f32_e32 v2, v33, v2
	v_cvt_pk_bf16_f32 v70, v18, v19
	v_cvt_pk_bf16_f32 v71, v20, v21
	v_cvt_pk_bf16_f32 v72, v22, v23
	v_cvt_pk_bf16_f32 v73, v24, v25
	v_cvt_pk_bf16_f32 v74, v26, v27
	v_cvt_pk_bf16_f32 v75, v28, v29
	v_cvt_pk_bf16_f32 v76, v30, v31
	v_cvt_pk_bf16_f32 v77, v32, v33
	s_waitcnt lgkmcnt(0)
	v_mfma_f32_32x32x16_bf16 v[34:49], v[98:101], v[70:73], v[34:49]
	v_add_f32_e32 v152, v152, v2
	v_mfma_f32_32x32x16_bf16 v[50:65], v[110:113], v[70:73], v[50:65]
	v_mfma_f32_32x32x16_bf16 v[34:49], v[102:105], v[74:77], v[34:49]
	v_mfma_f32_32x32x16_bf16 v[50:65], v[106:109], v[74:77], v[50:65]

.LBB0_761:
	v_add_u32_e32 v2, v168, v165
	s_waitcnt lgkmcnt(0)
	v_add_u32_e32 v4, v168, v166
	ds_read_b128 v[12:15], v2 offset:8192
	ds_read_b128 v[8:11], v4 offset:8192
	v_add_u32_e32 v2, v168, v163
	v_add_u32_e32 v4, v168, v164
	ds_read_b128 v[66:69], v2 offset:8192
	ds_read_b128 v[4:7], v4 offset:8192
	s_and_b64 vcc, exec, s[70:71]
	s_cbranch_vccnz .LBB0_765
	s_nop 0
	v_max_f32_e32 v2, v19, v19
	v_max_f32_e32 v16, v18, v18
	v_max_f32_e32 v2, v16, v2
	v_max3_f32 v2, v2, v20, v21
	v_max3_f32 v2, v2, v22, v23
	v_mbcnt_hi_u32_b32 v16, -1, v1
	v_max3_f32 v2, v2, v24, v25
	v_and_b32_e32 v70, 64, v16
	v_max3_f32 v2, v2, v26, v27
	v_xor_b32_e32 v17, 32, v16
	v_add_u32_e32 v70, 64, v70
	v_max3_f32 v2, v2, v28, v29
	v_cmp_lt_i32_e32 vcc, v17, v70
	v_max3_f32 v2, v2, v30, v31
	v_max3_f32 v2, v2, v32, v33
	v_cndmask_b32_e32 v16, v16, v17, vcc
	v_lshlrev_b32_e32 v16, 2, v16
	v_mov_b32_e32 v16, v2
	s_nop 1
	v_permlane32_swap_b32_e32 v16, v2
	s_nop 0
	v_max_f32_e32 v16, v16, v16
	v_max_f32_e32 v2, v2, v16
	v_mul_f32_e32 v2, 0x3fb8aa3b, v2
	v_add_f32_e32 v16, 0x41380000, v153
	v_cmp_gt_f32_e32 vcc, v2, v16
	s_cbranch_vccz .LBB0_764
	v_max_f32_e32 v2, v2, v2
	v_max_f32_e32 v16, v153, v153
	v_max_f32_e32 v16, v16, v2
	v_sub_f32_e32 v2, v153, v16
	v_exp_f32_e32 v2, v2
	v_mov_b32_e32 v153, v16
	v_pk_mul_f32 v[48:49], v[48:49], v[2:3] op_sel_hi:[1,0]
	v_pk_mul_f32 v[46:47], v[46:47], v[2:3] op_sel_hi:[1,0]
	v_pk_mul_f32 v[44:45], v[44:45], v[2:3] op_sel_hi:[1,0]
	v_pk_mul_f32 v[42:43], v[42:43], v[2:3] op_sel_hi:[1,0]
	v_pk_mul_f32 v[40:41], v[40:41], v[2:3] op_sel_hi:[1,0]
	v_pk_mul_f32 v[38:39], v[38:39], v[2:3] op_sel_hi:[1,0]
	v_pk_mul_f32 v[36:37], v[36:37], v[2:3] op_sel_hi:[1,0]
	v_pk_mul_f32 v[34:35], v[34:35], v[2:3] op_sel_hi:[1,0]
	v_pk_mul_f32 v[64:65], v[64:65], v[2:3] op_sel_hi:[1,0]
	v_pk_mul_f32 v[62:63], v[62:63], v[2:3] op_sel_hi:[1,0]
	v_pk_mul_f32 v[60:61], v[60:61], v[2:3] op_sel_hi:[1,0]
	v_pk_mul_f32 v[58:59], v[58:59], v[2:3] op_sel_hi:[1,0]
	v_pk_mul_f32 v[56:57], v[56:57], v[2:3] op_sel_hi:[1,0]
	v_pk_mul_f32 v[54:55], v[54:55], v[2:3] op_sel_hi:[1,0]
	v_pk_mul_f32 v[52:53], v[52:53], v[2:3] op_sel_hi:[1,0]
	v_pk_mul_f32 v[50:51], v[50:51], v[2:3] op_sel_hi:[1,0]
	v_mul_f32_e32 v152, v152, v2

.LBB0_767:
	v_add_u32_e32 v2, v167, v165
	s_waitcnt lgkmcnt(0)
	v_add_u32_e32 v4, v167, v166
	ds_read_b128 v[12:15], v2 offset:8192
	ds_read_b128 v[8:11], v4 offset:8192
	v_add_u32_e32 v2, v167, v163
	v_add_u32_e32 v4, v167, v164
	ds_read_b128 v[66:69], v2 offset:8192
	ds_read_b128 v[4:7], v4 offset:8192
	s_and_b64 vcc, exec, s[70:71]
	s_cbranch_vccnz .LBB0_771
	s_nop 0
	v_max_f32_e32 v2, v19, v19
	v_max_f32_e32 v16, v18, v18
	v_max_f32_e32 v2, v16, v2
	v_max3_f32 v2, v2, v20, v21
	v_max3_f32 v2, v2, v22, v23
	v_mbcnt_hi_u32_b32 v16, -1, v1
	v_max3_f32 v2, v2, v24, v25
	v_and_b32_e32 v70, 64, v16
	v_max3_f32 v2, v2, v26, v27
	v_xor_b32_e32 v17, 32, v16
	v_add_u32_e32 v70, 64, v70
	v_max3_f32 v2, v2, v28, v29
	v_cmp_lt_i32_e32 vcc, v17, v70
	v_max3_f32 v2, v2, v30, v31
	v_max3_f32 v2, v2, v32, v33
	v_cndmask_b32_e32 v16, v16, v17, vcc
	v_lshlrev_b32_e32 v16, 2, v16
	v_mov_b32_e32 v16, v2
	s_nop 1
	v_permlane32_swap_b32_e32 v16, v2
	s_nop 0
	v_max_f32_e32 v16, v16, v16
	v_max_f32_e32 v2, v2, v16
	v_mul_f32_e32 v2, 0x3fb8aa3b, v2
	v_add_f32_e32 v16, 0x41380000, v153
	v_cmp_gt_f32_e32 vcc, v2, v16
	s_cbranch_vccz .LBB0_770
	v_max_f32_e32 v2, v2, v2
	v_max_f32_e32 v16, v153, v153
	v_max_f32_e32 v16, v16, v2
	v_sub_f32_e32 v2, v153, v16
	v_exp_f32_e32 v2, v2
	v_mov_b32_e32 v153, v16
	v_pk_mul_f32 v[48:49], v[48:49], v[2:3] op_sel_hi:[1,0]
	v_pk_mul_f32 v[46:47], v[46:47], v[2:3] op_sel_hi:[1,0]
	v_pk_mul_f32 v[44:45], v[44:45], v[2:3] op_sel_hi:[1,0]
	v_pk_mul_f32 v[42:43], v[42:43], v[2:3] op_sel_hi:[1,0]
	v_pk_mul_f32 v[40:41], v[40:41], v[2:3] op_sel_hi:[1,0]
	v_pk_mul_f32 v[38:39], v[38:39], v[2:3] op_sel_hi:[1,0]
	v_pk_mul_f32 v[36:37], v[36:37], v[2:3] op_sel_hi:[1,0]
	v_pk_mul_f32 v[34:35], v[34:35], v[2:3] op_sel_hi:[1,0]
	v_pk_mul_f32 v[64:65], v[64:65], v[2:3] op_sel_hi:[1,0]
	v_pk_mul_f32 v[62:63], v[62:63], v[2:3] op_sel_hi:[1,0]
	v_pk_mul_f32 v[60:61], v[60:61], v[2:3] op_sel_hi:[1,0]
	v_pk_mul_f32 v[58:59], v[58:59], v[2:3] op_sel_hi:[1,0]
	v_pk_mul_f32 v[56:57], v[56:57], v[2:3] op_sel_hi:[1,0]
	v_pk_mul_f32 v[54:55], v[54:55], v[2:3] op_sel_hi:[1,0]
	v_pk_mul_f32 v[52:53], v[52:53], v[2:3] op_sel_hi:[1,0]
	v_pk_mul_f32 v[50:51], v[50:51], v[2:3] op_sel_hi:[1,0]
	v_mul_f32_e32 v152, v152, v2

.LBB0_820:
	v_add_u32_e32 v18, v170, v165
	v_add_u32_e32 v19, v170, v166
	ds_read_b128 v[106:109], v18 offset:8192
	ds_read_b128 v[102:105], v19 offset:8192
	v_add_u32_e32 v18, v170, v163
	v_add_u32_e32 v19, v170, v164
	ds_read_b128 v[110:113], v18 offset:8192
	ds_read_b128 v[98:101], v19 offset:8192
	s_andn2_b64 vcc, exec, s[4:5]
	s_cbranch_vccnz .LBB0_965
	s_nop 0
	v_max_f32_e32 v18, v3, v3
	v_max_f32_e32 v19, v2, v2
	v_max_f32_e32 v18, v19, v18
	v_max3_f32 v18, v18, v4, v5
	v_max3_f32 v18, v18, v6, v7
	v_mbcnt_hi_u32_b32 v19, -1, v1
	v_max3_f32 v18, v18, v8, v9
	v_and_b32_e32 v21, 64, v19
	v_max3_f32 v18, v18, v10, v11
	v_xor_b32_e32 v20, 32, v19
	v_add_u32_e32 v21, 64, v21
	v_max3_f32 v18, v18, v12, v13
	v_cmp_lt_i32_e32 vcc, v20, v21
	v_max3_f32 v18, v18, v14, v15
	v_max3_f32 v18, v18, v16, v17
	v_cndmask_b32_e32 v19, v19, v20, vcc
	v_lshlrev_b32_e32 v19, 2, v19
	v_mov_b32_e32 v19, v18
	s_nop 1
	v_permlane32_swap_b32_e32 v19, v18
	s_nop 0
	s_mov_b32 s4, 0xf149f2ca
	s_mov_b32 s1, 0x3fb8aa3b
	v_max_f32_e32 v19, v19, v19
	v_max_f32_e32 v18, v18, v19
	v_mul_f32_e32 v18, 0x3fb8aa3b, v18
	v_max_f32_e32 v19, 0xf149f2ca, v18
	v_sub_f32_e32 v20, 0xf149f2ca, v19
	v_exp_f32_e32 v20, v20
	v_cmp_lt_f32_e32 vcc, s4, v18
	s_cmp_eq_u64 vcc, 0
	s_cselect_b64 vcc, -1, 0
	v_mul_f32_e32 v18, 0, v20
	v_cndmask_b32_e64 v50, v18, 0, vcc
	v_mov_b32_e32 v18, 0xf149f2ca
	v_cndmask_b32_e32 v117, v19, v18, vcc
	v_fma_f32 v2, v2, s1, -v117
	v_fma_f32 v3, v3, s1, -v117
	v_exp_f32_e32 v2, v2
	v_fma_f32 v4, v4, s1, -v117
	v_exp_f32_e32 v3, v3
	v_fma_f32 v5, v5, s1, -v117
	v_exp_f32_e32 v4, v4
	v_fma_f32 v6, v6, s1, -v117
	v_exp_f32_e32 v5, v5
	v_fma_f32 v7, v7, s1, -v117
	v_exp_f32_e32 v6, v6
	v_cndmask_b32_e64 v2, 0, v2, s[44:45]
	v_fma_f32 v8, v8, s1, -v117
	v_exp_f32_e32 v7, v7
	v_cndmask_b32_e64 v3, 0, v3, s[42:43]
	v_add_f32_e32 v18, 0, v2
	v_fma_f32 v9, v9, s1, -v117
	v_exp_f32_e32 v8, v8
	v_cndmask_b32_e64 v4, 0, v4, s[40:41]
	v_add_f32_e32 v18, v3, v18
	v_fma_f32 v10, v10, s1, -v117
	v_exp_f32_e32 v9, v9
	v_cndmask_b32_e64 v5, 0, v5, s[38:39]
	v_add_f32_e32 v18, v4, v18
	v_fma_f32 v11, v11, s1, -v117
	v_exp_f32_e32 v10, v10
	v_cndmask_b32_e64 v6, 0, v6, s[52:53]
	v_add_f32_e32 v18, v5, v18
	v_fma_f32 v12, v12, s1, -v117
	v_exp_f32_e32 v11, v11
	v_cndmask_b32_e64 v7, 0, v7, s[50:51]
	v_add_f32_e32 v18, v6, v18
	v_fma_f32 v13, v13, s1, -v117
	v_exp_f32_e32 v12, v12
	v_cndmask_b32_e64 v8, 0, v8, s[48:49]
	v_add_f32_e32 v18, v7, v18
	v_fma_f32 v14, v14, s1, -v117
	v_exp_f32_e32 v13, v13
	v_cndmask_b32_e64 v9, 0, v9, s[46:47]
	v_add_f32_e32 v18, v8, v18
	v_fma_f32 v15, v15, s1, -v117
	v_exp_f32_e32 v14, v14
	v_cndmask_b32_e64 v10, 0, v10, s[60:61]
	v_add_f32_e32 v18, v9, v18
	v_fma_f32 v16, v16, s1, -v117
	v_exp_f32_e32 v15, v15
	v_cndmask_b32_e64 v11, 0, v11, s[58:59]
	v_add_f32_e32 v18, v10, v18
	v_fma_f32 v17, v17, s1, -v117
	v_exp_f32_e32 v16, v16
	v_cndmask_b32_e64 v12, 0, v12, s[56:57]
	v_add_f32_e32 v18, v11, v18
	v_exp_f32_e32 v17, v17
	v_cndmask_b32_e64 v13, 0, v13, s[54:55]
	v_add_f32_e32 v18, v12, v18
	v_cndmask_b32_e64 v14, 0, v14, s[68:69]
	v_add_f32_e32 v18, v13, v18
	v_cndmask_b32_e64 v15, 0, v15, s[66:67]
	v_add_f32_e32 v18, v14, v18
	v_cndmask_b32_e64 v16, 0, v16, s[64:65]
	v_add_f32_e32 v18, v15, v18
	v_cndmask_b32_e64 v17, 0, v17, s[62:63]
	v_add_f32_e32 v18, v16, v18
	v_add_f32_e32 v115, v17, v18
	v_mov_b32_e32 v51, v50
	v_mov_b32_e32 v52, v50
	v_mov_b32_e32 v53, v50
	v_mov_b32_e32 v54, v50
	v_mov_b32_e32 v55, v50
	v_mov_b32_e32 v56, v50
	v_mov_b32_e32 v57, v50
	v_mov_b32_e32 v58, v50
	v_mov_b32_e32 v59, v50
	v_mov_b32_e32 v60, v50
	v_mov_b32_e32 v61, v50
	v_mov_b32_e32 v62, v50
	v_mov_b32_e32 v63, v50
	v_mov_b32_e32 v64, v50
	v_mov_b32_e32 v65, v50
	v_cvt_pk_bf16_f32 v118, v2, v3
	v_cvt_pk_bf16_f32 v119, v4, v5
	v_cvt_pk_bf16_f32 v120, v6, v7
	v_cvt_pk_bf16_f32 v121, v8, v9
	v_cvt_pk_bf16_f32 v122, v10, v11
	v_cvt_pk_bf16_f32 v123, v12, v13
	v_cvt_pk_bf16_f32 v124, v14, v15
	v_cvt_pk_bf16_f32 v125, v16, v17
	v_mov_b64_e32 v[18:19], v[50:51]
	v_mov_b64_e32 v[20:21], v[52:53]
	v_mov_b64_e32 v[22:23], v[54:55]
	v_mov_b64_e32 v[24:25], v[56:57]
	v_mov_b64_e32 v[26:27], v[58:59]
	v_mov_b64_e32 v[28:29], v[60:61]
	v_mov_b64_e32 v[30:31], v[62:63]
	v_mov_b64_e32 v[32:33], v[64:65]
	s_waitcnt lgkmcnt(0)
	v_mfma_f32_32x32x16_bf16 v[34:49], v[82:85], v[118:121], v[50:65]
	v_add_f32_e32 v115, v50, v115
	v_mfma_f32_32x32x16_bf16 v[18:33], v[94:97], v[118:121], v[18:33]
	v_mfma_f32_32x32x16_bf16 v[34:49], v[86:89], v[122:125], v[34:49]
	v_mfma_f32_32x32x16_bf16 v[18:33], v[90:93], v[122:125], v[18:33]
	s_cmp_ge_i32 s13, s20
	s_cselect_b64 s[4:5], -1, 0
	s_cmp_lt_i32 s13, s20
	s_cbranch_scc0 .LBB0_966
	s_branch .LBB0_967

.LBB0_837:
	ds_read_b128 v[174:177], v36 offset:8192
	ds_read_b128 v[170:173], v35 offset:8192
	ds_read_b128 v[166:169], v34 offset:8192
	ds_read_b128 v[162:165], v221 offset:8192
	s_andn2_b64 vcc, exec, s[76:77]
	s_cbranch_vccnz .LBB0_839
	s_nop 4
	v_max_f32_e32 v2, v19, v19
	v_max_f32_e32 v4, v18, v18
	v_max_f32_e32 v2, v4, v2
	v_max3_f32 v2, v2, v20, v21
	v_max3_f32 v2, v2, v22, v23
	v_max3_f32 v2, v2, v24, v25
	v_and_b32_e32 v5, 64, v222
	v_max3_f32 v2, v2, v26, v27
	v_xor_b32_e32 v4, 32, v222
	v_add_u32_e32 v5, 64, v5
	v_max3_f32 v2, v2, v28, v29
	v_cmp_lt_i32_e32 vcc, v4, v5
	v_max3_f32 v2, v2, v30, v31
	v_max3_f32 v2, v2, v32, v33
	v_cndmask_b32_e32 v4, v222, v4, vcc
	v_lshlrev_b32_e32 v4, 2, v4
	v_mov_b32_e32 v4, v2
	s_nop 1
	v_permlane32_swap_b32_e32 v4, v2
	s_nop 0
	s_mov_b32 s76, 0xf149f2ca
	v_max_f32_e32 v4, v4, v4
	v_max_f32_e32 v2, v2, v4
	v_mul_f32_e32 v2, 0x3fb8aa3b, v2
	v_max_f32_e32 v4, 0xf149f2ca, v2
	v_sub_f32_e32 v5, 0xf149f2ca, v4
	v_exp_f32_e32 v5, v5
	v_cmp_lt_f32_e32 vcc, s76, v2
	s_cmp_eq_u64 vcc, 0
	s_cselect_b64 vcc, -1, 0
	v_mul_f32_e32 v2, 0, v5
	v_cndmask_b32_e32 v233, v4, v223, vcc
	v_cndmask_b32_e64 v66, v2, 0, vcc
	v_fma_f32 v2, v33, s5, -v233
	v_exp_f32_e32 v2, v2
	v_fma_f32 v4, v32, s5, -v233
	v_exp_f32_e32 v4, v4
	v_readlane_b32 s76, v254, 27
	v_fma_f32 v5, v31, s5, -v233
	v_readlane_b32 s77, v254, 28
	v_exp_f32_e32 v5, v5
	v_fma_f32 v6, v30, s5, -v233
	v_cndmask_b32_e64 v33, 0, v2, s[76:77]
	v_readlane_b32 s76, v254, 29
	v_readlane_b32 s77, v254, 30
	v_exp_f32_e32 v6, v6
	v_fma_f32 v2, v29, s5, -v233
	v_cndmask_b32_e64 v32, 0, v4, s[76:77]
	v_readlane_b32 s76, v254, 31
	v_readlane_b32 s77, v254, 32
	v_exp_f32_e32 v2, v2
	v_fma_f32 v4, v28, s5, -v233
	v_cndmask_b32_e64 v31, 0, v5, s[76:77]
	v_readlane_b32 s76, v254, 33
	v_readlane_b32 s77, v254, 34
	v_fma_f32 v5, v27, s5, -v233
	v_exp_f32_e32 v5, v5
	v_cndmask_b32_e64 v30, 0, v6, s[76:77]
	v_fma_f32 v6, v26, s5, -v233
	v_exp_f32_e32 v6, v6
	v_exp_f32_e32 v4, v4
	v_cndmask_b32_e64 v29, 0, v2, s[10:11]
	v_cndmask_b32_e64 v27, 0, v5, s[14:15]
	v_cndmask_b32_e64 v26, 0, v6, s[16:17]
	v_fma_f32 v6, v22, s5, -v233
	v_fma_f32 v2, v25, s5, -v233
	v_fma_f32 v5, v23, s5, -v233
	v_exp_f32_e32 v6, v6
	v_cndmask_b32_e64 v28, 0, v4, s[12:13]
	v_exp_f32_e32 v2, v2
	v_fma_f32 v4, v24, s5, -v233
	v_exp_f32_e32 v5, v5
	v_exp_f32_e32 v4, v4
	v_cndmask_b32_e64 v22, 0, v6, s[24:25]
	v_fma_f32 v6, v18, s5, -v233
	v_cndmask_b32_e64 v25, 0, v2, s[18:19]
	v_cndmask_b32_e64 v23, 0, v5, s[22:23]
	v_fma_f32 v2, v21, s5, -v233
	v_fma_f32 v5, v19, s5, -v233
	v_exp_f32_e32 v6, v6
	v_cndmask_b32_e64 v24, 0, v4, s[20:21]
	v_exp_f32_e32 v2, v2
	v_fma_f32 v4, v20, s5, -v233
	v_exp_f32_e32 v5, v5
	v_exp_f32_e32 v4, v4
	v_cndmask_b32_e64 v18, 0, v6, s[34:35]
	v_cndmask_b32_e64 v21, 0, v2, s[26:27]
	v_cndmask_b32_e64 v19, 0, v5, s[30:31]
	v_add_f32_e32 v2, 0, v18
	v_cndmask_b32_e64 v20, 0, v4, s[28:29]
	v_add_f32_e32 v2, v19, v2
	v_add_f32_e32 v2, v20, v2
	v_add_f32_e32 v2, v21, v2
	v_add_f32_e32 v2, v22, v2
	v_add_f32_e32 v2, v23, v2
	v_add_f32_e32 v2, v24, v2
	v_add_f32_e32 v2, v25, v2
	v_add_f32_e32 v2, v26, v2
	v_add_f32_e32 v2, v27, v2
	v_add_f32_e32 v2, v28, v2
	v_add_f32_e32 v2, v29, v2
	v_add_f32_e32 v2, v30, v2
	v_add_f32_e32 v2, v31, v2
	v_add_f32_e32 v2, v32, v2
	v_mov_b32_e32 v67, v66
	v_mov_b32_e32 v68, v66
	v_mov_b32_e32 v69, v66
	v_mov_b32_e32 v70, v66
	v_mov_b32_e32 v71, v66
	v_mov_b32_e32 v72, v66
	v_mov_b32_e32 v73, v66
	v_mov_b32_e32 v74, v66
	v_mov_b32_e32 v75, v66
	v_mov_b32_e32 v76, v66
	v_mov_b32_e32 v77, v66
	v_mov_b32_e32 v78, v66
	v_mov_b32_e32 v79, v66
	v_mov_b32_e32 v80, v66
	v_mov_b32_e32 v81, v66
	v_add_f32_e32 v2, v33, v2
	v_cvt_pk_bf16_f32 v4, v18, v19
	v_cvt_pk_bf16_f32 v5, v20, v21
	v_cvt_pk_bf16_f32 v6, v22, v23
	v_cvt_pk_bf16_f32 v7, v24, v25
	v_cvt_pk_bf16_f32 v8, v26, v27
	v_cvt_pk_bf16_f32 v9, v28, v29
	v_cvt_pk_bf16_f32 v10, v30, v31
	v_cvt_pk_bf16_f32 v11, v32, v33
	v_mov_b64_e32 v[50:51], v[66:67]
	v_mov_b64_e32 v[52:53], v[68:69]
	v_mov_b64_e32 v[54:55], v[70:71]
	v_mov_b64_e32 v[56:57], v[72:73]
	v_mov_b64_e32 v[58:59], v[74:75]
	v_mov_b64_e32 v[60:61], v[76:77]
	v_mov_b64_e32 v[62:63], v[78:79]
	v_mov_b64_e32 v[64:65], v[80:81]
	s_waitcnt lgkmcnt(0)
	v_mfma_f32_32x32x16_bf16 v[34:49], v[146:149], v[4:7], v[66:81]
	v_add_f32_e32 v232, v66, v2
	v_mfma_f32_32x32x16_bf16 v[50:65], v[158:161], v[4:7], v[50:65]
	v_mfma_f32_32x32x16_bf16 v[34:49], v[150:153], v[8:11], v[34:49]
	v_mfma_f32_32x32x16_bf16 v[50:65], v[154:157], v[8:11], v[50:65]
	s_cmp_ge_i32 s89, s9
	s_cselect_b64 s[76:77], -1, 0
	s_cmp_lt_i32 s89, s9
	s_cbranch_scc0 .LBB0_840
	s_branch .LBB0_841

.Lb5mid_go:
	v_add_u32_e32 v2, v210, v200
	v_add_u32_e32 v4, v210, v201
	ds_read_b128 v[12:15], v2 offset:8192
	ds_read_b128 v[8:11], v4 offset:8192
	v_add_u32_e32 v2, v210, v202
	v_add_u32_e32 v4, v210, v203
	ds_read_b128 v[66:69], v2 offset:8192
	ds_read_b128 v[4:7], v4 offset:8192
	s_andn2_b64 vcc, exec, s[76:77]
	s_cbranch_vccnz .LBB0_845
	s_nop 1
	v_max_f32_e32 v2, v19, v19
	v_max_f32_e32 v16, v18, v18
	v_max_f32_e32 v2, v16, v2
	v_max3_f32 v2, v2, v20, v21
	v_max3_f32 v2, v2, v22, v23
	v_mbcnt_hi_u32_b32 v16, -1, v1
	v_max3_f32 v2, v2, v24, v25
	v_and_b32_e32 v70, 64, v16
	v_max3_f32 v2, v2, v26, v27
	v_xor_b32_e32 v17, 32, v16
	v_add_u32_e32 v70, 64, v70
	v_max3_f32 v2, v2, v28, v29
	v_cmp_lt_i32_e32 vcc, v17, v70
	v_max3_f32 v2, v2, v30, v31
	v_max3_f32 v2, v2, v32, v33
	v_cndmask_b32_e32 v16, v16, v17, vcc
	v_lshlrev_b32_e32 v16, 2, v16
	v_mov_b32_e32 v16, v2
	s_nop 1
	v_permlane32_swap_b32_e32 v16, v2
	s_nop 0
	v_max_f32_e32 v16, v16, v16
	v_max_f32_e32 v2, v2, v16
	v_mul_f32_e32 v2, 0x3fb8aa3b, v2
	v_add_f32_e32 v16, 0x41380000, v233
	v_cmp_gt_f32_e32 vcc, v2, v16
	s_cbranch_vccz .LBB0_844
	v_max_f32_e32 v2, v2, v2
	v_max_f32_e32 v16, v233, v233
	v_max_f32_e32 v16, v16, v2
	v_sub_f32_e32 v2, v233, v16
	v_exp_f32_e32 v2, v2
	v_mov_b32_e32 v233, v16
	v_pk_mul_f32 v[48:49], v[48:49], v[2:3] op_sel_hi:[1,0]
	v_pk_mul_f32 v[46:47], v[46:47], v[2:3] op_sel_hi:[1,0]
	v_pk_mul_f32 v[44:45], v[44:45], v[2:3] op_sel_hi:[1,0]
	v_pk_mul_f32 v[42:43], v[42:43], v[2:3] op_sel_hi:[1,0]
	v_pk_mul_f32 v[40:41], v[40:41], v[2:3] op_sel_hi:[1,0]
	v_pk_mul_f32 v[38:39], v[38:39], v[2:3] op_sel_hi:[1,0]
	v_pk_mul_f32 v[36:37], v[36:37], v[2:3] op_sel_hi:[1,0]
	v_pk_mul_f32 v[34:35], v[34:35], v[2:3] op_sel_hi:[1,0]
	v_pk_mul_f32 v[64:65], v[64:65], v[2:3] op_sel_hi:[1,0]
	v_pk_mul_f32 v[62:63], v[62:63], v[2:3] op_sel_hi:[1,0]
	v_pk_mul_f32 v[60:61], v[60:61], v[2:3] op_sel_hi:[1,0]
	v_pk_mul_f32 v[58:59], v[58:59], v[2:3] op_sel_hi:[1,0]
	v_pk_mul_f32 v[56:57], v[56:57], v[2:3] op_sel_hi:[1,0]
	v_pk_mul_f32 v[54:55], v[54:55], v[2:3] op_sel_hi:[1,0]
	v_pk_mul_f32 v[52:53], v[52:53], v[2:3] op_sel_hi:[1,0]
	v_pk_mul_f32 v[50:51], v[50:51], v[2:3] op_sel_hi:[1,0]
	v_mul_f32_e32 v232, v232, v2
.LBB0_844:
	v_fma_f32 v2, v33, s5, -v233
	v_exp_f32_e32 v33, v2
	v_fma_f32 v2, v32, s5, -v233
	v_exp_f32_e32 v32, v2
	v_fma_f32 v2, v31, s5, -v233
	v_exp_f32_e32 v31, v2
	v_fma_f32 v2, v30, s5, -v233
	v_exp_f32_e32 v30, v2
	v_fma_f32 v2, v29, s5, -v233
	v_exp_f32_e32 v29, v2
	v_fma_f32 v2, v28, s5, -v233
	v_exp_f32_e32 v28, v2
	v_fma_f32 v2, v27, s5, -v233
	v_exp_f32_e32 v27, v2
	v_fma_f32 v2, v26, s5, -v233
	v_exp_f32_e32 v26, v2
	v_fma_f32 v2, v25, s5, -v233
	v_exp_f32_e32 v25, v2
	v_fma_f32 v2, v24, s5, -v233
	v_fma_f32 v18, v18, s5, -v233
	v_exp_f32_e32 v24, v2
	v_fma_f32 v2, v23, s5, -v233
	v_fma_f32 v17, v19, s5, -v233
	v_exp_f32_e32 v18, v18
	v_exp_f32_e32 v23, v2
	v_fma_f32 v2, v22, s5, -v233
	v_fma_f32 v16, v20, s5, -v233
	v_exp_f32_e32 v19, v17
	v_exp_f32_e32 v22, v2
	v_fma_f32 v2, v21, s5, -v233
	v_exp_f32_e32 v20, v16
	v_exp_f32_e32 v21, v2
	v_add_f32_e32 v2, 0, v18
	v_add_f32_e32 v2, v19, v2
	v_add_f32_e32 v2, v20, v2
	v_add_f32_e32 v2, v21, v2
	v_add_f32_e32 v2, v22, v2
	v_add_f32_e32 v2, v23, v2
	v_add_f32_e32 v2, v24, v2
	v_add_f32_e32 v2, v25, v2
	v_add_f32_e32 v2, v26, v2
	v_add_f32_e32 v2, v27, v2
	v_add_f32_e32 v2, v28, v2
	v_add_f32_e32 v2, v29, v2
	v_add_f32_e32 v2, v30, v2
	v_add_f32_e32 v2, v31, v2
	v_add_f32_e32 v2, v32, v2
	v_add_f32_e32 v2, v33, v2
	v_cvt_pk_bf16_f32 v70, v18, v19
	v_cvt_pk_bf16_f32 v71, v20, v21
	v_cvt_pk_bf16_f32 v72, v22, v23
	v_cvt_pk_bf16_f32 v73, v24, v25
	v_cvt_pk_bf16_f32 v74, v26, v27
	v_cvt_pk_bf16_f32 v75, v28, v29
	v_cvt_pk_bf16_f32 v76, v30, v31
	v_cvt_pk_bf16_f32 v77, v32, v33
	s_waitcnt lgkmcnt(0)
	v_mfma_f32_32x32x16_bf16 v[34:49], v[146:149], v[70:73], v[34:49]
	v_add_f32_e32 v232, v232, v2
	v_mfma_f32_32x32x16_bf16 v[50:65], v[158:161], v[70:73], v[50:65]
	v_mfma_f32_32x32x16_bf16 v[34:49], v[150:153], v[74:77], v[34:49]
	v_mfma_f32_32x32x16_bf16 v[50:65], v[154:157], v[74:77], v[50:65]

.LBB0_847:
	v_add_u32_e32 v2, v211, v200
	s_waitcnt lgkmcnt(0)
	v_add_u32_e32 v4, v211, v201
	ds_read_b128 v[12:15], v2 offset:8192
	ds_read_b128 v[8:11], v4 offset:8192
	v_add_u32_e32 v2, v211, v202
	v_add_u32_e32 v4, v211, v203
	ds_read_b128 v[66:69], v2 offset:8192
	ds_read_b128 v[4:7], v4 offset:8192
	s_andn2_b64 vcc, exec, s[76:77]
	s_cbranch_vccnz .LBB0_851
	s_nop 0
	v_max_f32_e32 v2, v19, v19
	v_max_f32_e32 v16, v18, v18
	v_max_f32_e32 v2, v16, v2
	v_max3_f32 v2, v2, v20, v21
	v_max3_f32 v2, v2, v22, v23
	v_mbcnt_hi_u32_b32 v16, -1, v1
	v_max3_f32 v2, v2, v24, v25
	v_and_b32_e32 v70, 64, v16
	v_max3_f32 v2, v2, v26, v27
	v_xor_b32_e32 v17, 32, v16
	v_add_u32_e32 v70, 64, v70
	v_max3_f32 v2, v2, v28, v29
	v_cmp_lt_i32_e32 vcc, v17, v70
	v_max3_f32 v2, v2, v30, v31
	v_max3_f32 v2, v2, v32, v33
	v_cndmask_b32_e32 v16, v16, v17, vcc
	v_lshlrev_b32_e32 v16, 2, v16
	v_mov_b32_e32 v16, v2
	s_nop 1
	v_permlane32_swap_b32_e32 v16, v2
	s_nop 0
	v_max_f32_e32 v16, v16, v16
	v_max_f32_e32 v2, v2, v16
	v_mul_f32_e32 v2, 0x3fb8aa3b, v2
	v_add_f32_e32 v16, 0x41380000, v233
	v_cmp_gt_f32_e32 vcc, v2, v16
	s_cbranch_vccz .LBB0_850
	v_max_f32_e32 v2, v2, v2
	v_max_f32_e32 v16, v233, v233
	v_max_f32_e32 v16, v16, v2
	v_sub_f32_e32 v2, v233, v16
	v_exp_f32_e32 v2, v2
	v_mov_b32_e32 v233, v16
	v_pk_mul_f32 v[48:49], v[48:49], v[2:3] op_sel_hi:[1,0]
	v_pk_mul_f32 v[46:47], v[46:47], v[2:3] op_sel_hi:[1,0]
	v_pk_mul_f32 v[44:45], v[44:45], v[2:3] op_sel_hi:[1,0]
	v_pk_mul_f32 v[42:43], v[42:43], v[2:3] op_sel_hi:[1,0]
	v_pk_mul_f32 v[40:41], v[40:41], v[2:3] op_sel_hi:[1,0]
	v_pk_mul_f32 v[38:39], v[38:39], v[2:3] op_sel_hi:[1,0]
	v_pk_mul_f32 v[36:37], v[36:37], v[2:3] op_sel_hi:[1,0]
	v_pk_mul_f32 v[34:35], v[34:35], v[2:3] op_sel_hi:[1,0]
	v_pk_mul_f32 v[64:65], v[64:65], v[2:3] op_sel_hi:[1,0]
	v_pk_mul_f32 v[62:63], v[62:63], v[2:3] op_sel_hi:[1,0]
	v_pk_mul_f32 v[60:61], v[60:61], v[2:3] op_sel_hi:[1,0]
	v_pk_mul_f32 v[58:59], v[58:59], v[2:3] op_sel_hi:[1,0]
	v_pk_mul_f32 v[56:57], v[56:57], v[2:3] op_sel_hi:[1,0]
	v_pk_mul_f32 v[54:55], v[54:55], v[2:3] op_sel_hi:[1,0]
	v_pk_mul_f32 v[52:53], v[52:53], v[2:3] op_sel_hi:[1,0]
	v_pk_mul_f32 v[50:51], v[50:51], v[2:3] op_sel_hi:[1,0]
	v_mul_f32_e32 v232, v232, v2

.LBB0_853:
	v_add_u32_e32 v2, v212, v200
	s_waitcnt lgkmcnt(0)
	v_add_u32_e32 v4, v212, v201
	ds_read_b128 v[12:15], v2 offset:8192
	ds_read_b128 v[8:11], v4 offset:8192
	v_add_u32_e32 v2, v212, v202
	v_add_u32_e32 v4, v212, v203
	ds_read_b128 v[66:69], v2 offset:8192
	ds_read_b128 v[4:7], v4 offset:8192
	s_andn2_b64 vcc, exec, s[76:77]
	s_cbranch_vccnz .LBB0_857
	s_nop 0
	v_max_f32_e32 v2, v19, v19
	v_max_f32_e32 v16, v18, v18
	v_max_f32_e32 v2, v16, v2
	v_max3_f32 v2, v2, v20, v21
	v_max3_f32 v2, v2, v22, v23
	v_mbcnt_hi_u32_b32 v16, -1, v1
	v_max3_f32 v2, v2, v24, v25
	v_and_b32_e32 v70, 64, v16
	v_max3_f32 v2, v2, v26, v27
	v_xor_b32_e32 v17, 32, v16
	v_add_u32_e32 v70, 64, v70
	v_max3_f32 v2, v2, v28, v29
	v_cmp_lt_i32_e32 vcc, v17, v70
	v_max3_f32 v2, v2, v30, v31
	v_max3_f32 v2, v2, v32, v33
	v_cndmask_b32_e32 v16, v16, v17, vcc
	v_lshlrev_b32_e32 v16, 2, v16
	v_mov_b32_e32 v16, v2
	s_nop 1
	v_permlane32_swap_b32_e32 v16, v2
	s_nop 0
	v_max_f32_e32 v16, v16, v16
	v_max_f32_e32 v2, v2, v16
	v_mul_f32_e32 v2, 0x3fb8aa3b, v2
	v_add_f32_e32 v16, 0x41380000, v233
	v_cmp_gt_f32_e32 vcc, v2, v16
	s_cbranch_vccz .LBB0_856
	v_max_f32_e32 v2, v2, v2
	v_max_f32_e32 v16, v233, v233
	v_max_f32_e32 v16, v16, v2
	v_sub_f32_e32 v2, v233, v16
	v_exp_f32_e32 v2, v2
	v_mov_b32_e32 v233, v16
	v_pk_mul_f32 v[48:49], v[48:49], v[2:3] op_sel_hi:[1,0]
	v_pk_mul_f32 v[46:47], v[46:47], v[2:3] op_sel_hi:[1,0]
	v_pk_mul_f32 v[44:45], v[44:45], v[2:3] op_sel_hi:[1,0]
	v_pk_mul_f32 v[42:43], v[42:43], v[2:3] op_sel_hi:[1,0]
	v_pk_mul_f32 v[40:41], v[40:41], v[2:3] op_sel_hi:[1,0]
	v_pk_mul_f32 v[38:39], v[38:39], v[2:3] op_sel_hi:[1,0]
	v_pk_mul_f32 v[36:37], v[36:37], v[2:3] op_sel_hi:[1,0]
	v_pk_mul_f32 v[34:35], v[34:35], v[2:3] op_sel_hi:[1,0]
	v_pk_mul_f32 v[64:65], v[64:65], v[2:3] op_sel_hi:[1,0]
	v_pk_mul_f32 v[62:63], v[62:63], v[2:3] op_sel_hi:[1,0]
	v_pk_mul_f32 v[60:61], v[60:61], v[2:3] op_sel_hi:[1,0]
	v_pk_mul_f32 v[58:59], v[58:59], v[2:3] op_sel_hi:[1,0]
	v_pk_mul_f32 v[56:57], v[56:57], v[2:3] op_sel_hi:[1,0]
	v_pk_mul_f32 v[54:55], v[54:55], v[2:3] op_sel_hi:[1,0]
	v_pk_mul_f32 v[52:53], v[52:53], v[2:3] op_sel_hi:[1,0]
	v_pk_mul_f32 v[50:51], v[50:51], v[2:3] op_sel_hi:[1,0]
	v_mul_f32_e32 v232, v232, v2

.LBB0_967:
	v_add_u32_e32 v50, v169, v165
	v_add_u32_e32 v51, v169, v166
	ds_read_b128 v[58:61], v50 offset:8192
	ds_read_b128 v[54:57], v51 offset:8192
	v_add_u32_e32 v50, v169, v163
	v_add_u32_e32 v51, v169, v164
	ds_read_b128 v[62:65], v50 offset:8192
	ds_read_b128 v[50:53], v51 offset:8192
	s_andn2_b64 vcc, exec, s[4:5]
	s_cbranch_vccnz .LBB0_971
	s_waitcnt lgkmcnt(4)
	s_nop 0
	v_max_f32_e32 v98, v3, v3
	v_max_f32_e32 v99, v2, v2
	v_max_f32_e32 v98, v99, v98
	v_max3_f32 v98, v98, v4, v5
	v_max3_f32 v98, v98, v6, v7
	v_mbcnt_hi_u32_b32 v99, -1, v1
	v_max3_f32 v98, v98, v8, v9
	v_and_b32_e32 v101, 64, v99
	v_max3_f32 v98, v98, v10, v11
	v_xor_b32_e32 v100, 32, v99
	v_add_u32_e32 v101, 64, v101
	v_max3_f32 v98, v98, v12, v13
	v_cmp_lt_i32_e32 vcc, v100, v101
	v_max3_f32 v98, v98, v14, v15
	v_max3_f32 v98, v98, v16, v17
	v_cndmask_b32_e32 v99, v99, v100, vcc
	v_lshlrev_b32_e32 v99, 2, v99
	v_mov_b32_e32 v99, v98
	s_nop 1
	v_permlane32_swap_b32_e32 v99, v98
	s_nop 0
	s_mov_b32 s1, 0x3fb8aa3b
	v_max_f32_e32 v99, v99, v99
	v_max_f32_e32 v98, v98, v99
	v_mul_f32_e32 v98, 0x3fb8aa3b, v98
	v_add_f32_e32 v99, 0x41380000, v117
	v_cmp_gt_f32_e32 vcc, v98, v99
	s_cbranch_vccz .LBB0_970
	v_max_f32_e32 v98, v98, v98
	v_max_f32_e32 v99, v117, v117
	v_max_f32_e32 v99, v99, v98
	v_sub_f32_e32 v98, v117, v99
	v_exp_f32_e32 v98, v98
	v_mov_b32_e32 v117, v99
	v_pk_mul_f32 v[48:49], v[48:49], v[98:99] op_sel_hi:[1,0]
	v_pk_mul_f32 v[46:47], v[46:47], v[98:99] op_sel_hi:[1,0]
	v_pk_mul_f32 v[44:45], v[44:45], v[98:99] op_sel_hi:[1,0]
	v_pk_mul_f32 v[42:43], v[42:43], v[98:99] op_sel_hi:[1,0]
	v_pk_mul_f32 v[40:41], v[40:41], v[98:99] op_sel_hi:[1,0]
	v_pk_mul_f32 v[38:39], v[38:39], v[98:99] op_sel_hi:[1,0]
	v_pk_mul_f32 v[36:37], v[36:37], v[98:99] op_sel_hi:[1,0]
	v_pk_mul_f32 v[34:35], v[34:35], v[98:99] op_sel_hi:[1,0]
	v_pk_mul_f32 v[32:33], v[32:33], v[98:99] op_sel_hi:[1,0]
	v_pk_mul_f32 v[30:31], v[30:31], v[98:99] op_sel_hi:[1,0]
	v_pk_mul_f32 v[28:29], v[28:29], v[98:99] op_sel_hi:[1,0]
	v_pk_mul_f32 v[26:27], v[26:27], v[98:99] op_sel_hi:[1,0]
	v_pk_mul_f32 v[24:25], v[24:25], v[98:99] op_sel_hi:[1,0]
	v_pk_mul_f32 v[22:23], v[22:23], v[98:99] op_sel_hi:[1,0]
	v_pk_mul_f32 v[20:21], v[20:21], v[98:99] op_sel_hi:[1,0]
	v_pk_mul_f32 v[18:19], v[18:19], v[98:99] op_sel_hi:[1,0]
	v_mul_f32_e32 v115, v115, v98
.LBB0_970:
	v_fma_f32 v2, v2, s1, -v117
	v_fma_f32 v3, v3, s1, -v117
	v_exp_f32_e32 v2, v2
	v_fma_f32 v4, v4, s1, -v117
	v_exp_f32_e32 v3, v3
	v_fma_f32 v5, v5, s1, -v117
	v_exp_f32_e32 v4, v4
	v_fma_f32 v6, v6, s1, -v117
	v_exp_f32_e32 v5, v5
	v_fma_f32 v7, v7, s1, -v117
	v_exp_f32_e32 v6, v6
	v_add_f32_e32 v98, 0, v2
	v_fma_f32 v8, v8, s1, -v117
	v_exp_f32_e32 v7, v7
	v_add_f32_e32 v98, v3, v98
	v_fma_f32 v9, v9, s1, -v117
	v_exp_f32_e32 v8, v8
	v_add_f32_e32 v98, v4, v98
	v_fma_f32 v10, v10, s1, -v117
	v_exp_f32_e32 v9, v9
	v_add_f32_e32 v98, v5, v98
	v_fma_f32 v11, v11, s1, -v117
	v_exp_f32_e32 v10, v10
	v_add_f32_e32 v98, v6, v98
	v_fma_f32 v12, v12, s1, -v117
	v_exp_f32_e32 v11, v11
	v_add_f32_e32 v98, v7, v98
	v_fma_f32 v13, v13, s1, -v117
	v_exp_f32_e32 v12, v12
	v_add_f32_e32 v98, v8, v98
	v_fma_f32 v14, v14, s1, -v117
	v_exp_f32_e32 v13, v13
	v_add_f32_e32 v98, v9, v98
	v_fma_f32 v15, v15, s1, -v117
	v_exp_f32_e32 v14, v14
	v_add_f32_e32 v98, v10, v98
	v_fma_f32 v16, v16, s1, -v117
	v_exp_f32_e32 v15, v15
	v_add_f32_e32 v98, v11, v98
	v_fma_f32 v17, v17, s1, -v117
	v_exp_f32_e32 v16, v16
	v_add_f32_e32 v98, v12, v98
	v_exp_f32_e32 v17, v17
	v_add_f32_e32 v98, v13, v98
	v_add_f32_e32 v98, v14, v98
	v_add_f32_e32 v98, v15, v98
	v_add_f32_e32 v98, v16, v98
	v_add_f32_e32 v106, v17, v98
	v_cvt_pk_bf16_f32 v98, v2, v3
	v_cvt_pk_bf16_f32 v99, v4, v5
	v_cvt_pk_bf16_f32 v100, v6, v7
	v_cvt_pk_bf16_f32 v101, v8, v9
	v_cvt_pk_bf16_f32 v102, v10, v11
	v_cvt_pk_bf16_f32 v103, v12, v13
	v_cvt_pk_bf16_f32 v104, v14, v15
	v_cvt_pk_bf16_f32 v105, v16, v17
	s_waitcnt lgkmcnt(0)
	v_mfma_f32_32x32x16_bf16 v[34:49], v[82:85], v[98:101], v[34:49]
	v_add_f32_e32 v115, v115, v106
	v_mfma_f32_32x32x16_bf16 v[18:33], v[94:97], v[98:101], v[18:33]
	v_mfma_f32_32x32x16_bf16 v[34:49], v[86:89], v[102:105], v[34:49]
	v_mfma_f32_32x32x16_bf16 v[18:33], v[90:93], v[102:105], v[18:33]

.LBB0_973:
	s_waitcnt lgkmcnt(0)
	v_add_u32_e32 v50, v168, v165
	v_add_u32_e32 v51, v168, v166
	ds_read_b128 v[58:61], v50 offset:8192
	ds_read_b128 v[54:57], v51 offset:8192
	v_add_u32_e32 v50, v168, v163
	v_add_u32_e32 v51, v168, v164
	ds_read_b128 v[62:65], v50 offset:8192
	ds_read_b128 v[50:53], v51 offset:8192
	s_andn2_b64 vcc, exec, s[4:5]
	s_cbranch_vccnz .LBB0_977
	s_nop 0
	v_max_f32_e32 v98, v3, v3
	v_max_f32_e32 v99, v2, v2
	v_max_f32_e32 v98, v99, v98
	v_max3_f32 v98, v98, v4, v5
	v_max3_f32 v98, v98, v6, v7
	v_mbcnt_hi_u32_b32 v99, -1, v1
	v_max3_f32 v98, v98, v8, v9
	v_and_b32_e32 v101, 64, v99
	v_max3_f32 v98, v98, v10, v11
	v_xor_b32_e32 v100, 32, v99
	v_add_u32_e32 v101, 64, v101
	v_max3_f32 v98, v98, v12, v13
	v_cmp_lt_i32_e32 vcc, v100, v101
	v_max3_f32 v98, v98, v14, v15
	v_max3_f32 v98, v98, v16, v17
	v_cndmask_b32_e32 v99, v99, v100, vcc
	v_lshlrev_b32_e32 v99, 2, v99
	v_mov_b32_e32 v99, v98
	s_nop 1
	v_permlane32_swap_b32_e32 v99, v98
	s_nop 0
	s_mov_b32 s1, 0x3fb8aa3b
	v_max_f32_e32 v99, v99, v99
	v_max_f32_e32 v98, v98, v99
	v_mul_f32_e32 v98, 0x3fb8aa3b, v98
	v_add_f32_e32 v99, 0x41380000, v117
	v_cmp_gt_f32_e32 vcc, v98, v99
	s_cbranch_vccz .LBB0_976
	v_max_f32_e32 v98, v98, v98
	v_max_f32_e32 v99, v117, v117
	v_max_f32_e32 v99, v99, v98
	v_sub_f32_e32 v98, v117, v99
	v_exp_f32_e32 v98, v98
	v_mov_b32_e32 v117, v99
	v_pk_mul_f32 v[48:49], v[48:49], v[98:99] op_sel_hi:[1,0]
	v_pk_mul_f32 v[46:47], v[46:47], v[98:99] op_sel_hi:[1,0]
	v_pk_mul_f32 v[44:45], v[44:45], v[98:99] op_sel_hi:[1,0]
	v_pk_mul_f32 v[42:43], v[42:43], v[98:99] op_sel_hi:[1,0]
	v_pk_mul_f32 v[40:41], v[40:41], v[98:99] op_sel_hi:[1,0]
	v_pk_mul_f32 v[38:39], v[38:39], v[98:99] op_sel_hi:[1,0]
	v_pk_mul_f32 v[36:37], v[36:37], v[98:99] op_sel_hi:[1,0]
	v_pk_mul_f32 v[34:35], v[34:35], v[98:99] op_sel_hi:[1,0]
	v_pk_mul_f32 v[32:33], v[32:33], v[98:99] op_sel_hi:[1,0]
	v_pk_mul_f32 v[30:31], v[30:31], v[98:99] op_sel_hi:[1,0]
	v_pk_mul_f32 v[28:29], v[28:29], v[98:99] op_sel_hi:[1,0]
	v_pk_mul_f32 v[26:27], v[26:27], v[98:99] op_sel_hi:[1,0]
	v_pk_mul_f32 v[24:25], v[24:25], v[98:99] op_sel_hi:[1,0]
	v_pk_mul_f32 v[22:23], v[22:23], v[98:99] op_sel_hi:[1,0]
	v_pk_mul_f32 v[20:21], v[20:21], v[98:99] op_sel_hi:[1,0]
	v_pk_mul_f32 v[18:19], v[18:19], v[98:99] op_sel_hi:[1,0]
	v_mul_f32_e32 v115, v115, v98

.LBB0_979:
	s_waitcnt lgkmcnt(0)
	v_add_u32_e32 v50, v167, v165
	v_add_u32_e32 v51, v167, v166
	ds_read_b128 v[58:61], v50 offset:8192
	ds_read_b128 v[54:57], v51 offset:8192
	v_add_u32_e32 v50, v167, v163
	v_add_u32_e32 v51, v167, v164
	ds_read_b128 v[62:65], v50 offset:8192
	ds_read_b128 v[50:53], v51 offset:8192
	s_andn2_b64 vcc, exec, s[4:5]
	s_cbranch_vccnz .LBB0_983
	s_nop 0
	v_max_f32_e32 v98, v3, v3
	v_max_f32_e32 v99, v2, v2
	v_max_f32_e32 v98, v99, v98
	v_max3_f32 v98, v98, v4, v5
	v_max3_f32 v98, v98, v6, v7
	v_mbcnt_hi_u32_b32 v99, -1, v1
	v_max3_f32 v98, v98, v8, v9
	v_and_b32_e32 v101, 64, v99
	v_max3_f32 v98, v98, v10, v11
	v_xor_b32_e32 v100, 32, v99
	v_add_u32_e32 v101, 64, v101
	v_max3_f32 v98, v98, v12, v13
	v_cmp_lt_i32_e32 vcc, v100, v101
	v_max3_f32 v98, v98, v14, v15
	v_max3_f32 v98, v98, v16, v17
	v_cndmask_b32_e32 v99, v99, v100, vcc
	v_lshlrev_b32_e32 v99, 2, v99
	v_mov_b32_e32 v99, v98
	s_nop 1
	v_permlane32_swap_b32_e32 v99, v98
	s_nop 0
	s_mov_b32 s1, 0x3fb8aa3b
	v_max_f32_e32 v99, v99, v99
	v_max_f32_e32 v98, v98, v99
	v_mul_f32_e32 v98, 0x3fb8aa3b, v98
	v_add_f32_e32 v99, 0x41380000, v117
	v_cmp_gt_f32_e32 vcc, v98, v99
	s_cbranch_vccz .LBB0_982
	v_max_f32_e32 v98, v98, v98
	v_max_f32_e32 v99, v117, v117
	v_max_f32_e32 v99, v99, v98
	v_sub_f32_e32 v98, v117, v99
	v_exp_f32_e32 v98, v98
	v_mov_b32_e32 v117, v99
	v_pk_mul_f32 v[48:49], v[48:49], v[98:99] op_sel_hi:[1,0]
	v_pk_mul_f32 v[46:47], v[46:47], v[98:99] op_sel_hi:[1,0]
	v_pk_mul_f32 v[44:45], v[44:45], v[98:99] op_sel_hi:[1,0]
	v_pk_mul_f32 v[42:43], v[42:43], v[98:99] op_sel_hi:[1,0]
	v_pk_mul_f32 v[40:41], v[40:41], v[98:99] op_sel_hi:[1,0]
	v_pk_mul_f32 v[38:39], v[38:39], v[98:99] op_sel_hi:[1,0]
	v_pk_mul_f32 v[36:37], v[36:37], v[98:99] op_sel_hi:[1,0]
	v_pk_mul_f32 v[34:35], v[34:35], v[98:99] op_sel_hi:[1,0]
	v_pk_mul_f32 v[32:33], v[32:33], v[98:99] op_sel_hi:[1,0]
	v_pk_mul_f32 v[30:31], v[30:31], v[98:99] op_sel_hi:[1,0]
	v_pk_mul_f32 v[28:29], v[28:29], v[98:99] op_sel_hi:[1,0]
	v_pk_mul_f32 v[26:27], v[26:27], v[98:99] op_sel_hi:[1,0]
	v_pk_mul_f32 v[24:25], v[24:25], v[98:99] op_sel_hi:[1,0]
	v_pk_mul_f32 v[22:23], v[22:23], v[98:99] op_sel_hi:[1,0]
	v_pk_mul_f32 v[20:21], v[20:21], v[98:99] op_sel_hi:[1,0]
	v_pk_mul_f32 v[18:19], v[18:19], v[98:99] op_sel_hi:[1,0]
	v_mul_f32_e32 v115, v115, v98

.LBB0_1002:
	ds_read_b128 v[110:113], v21 offset:8192
	ds_read_b128 v[106:109], v20 offset:8192
	ds_read_b128 v[102:105], v19 offset:8192
	ds_read_b128 v[98:101], v18 offset:8192
	s_andn2_b64 vcc, exec, s[4:5]
	s_cbranch_vccnz .LBB0_1004
	s_nop 4
	v_max_f32_e32 v18, v3, v3
	v_max_f32_e32 v19, v2, v2
	v_max_f32_e32 v18, v19, v18
	v_max3_f32 v18, v18, v4, v5
	v_max3_f32 v18, v18, v6, v7
	v_mbcnt_hi_u32_b32 v19, -1, v1
	v_max3_f32 v18, v18, v8, v9
	v_and_b32_e32 v21, 64, v19
	v_max3_f32 v18, v18, v10, v11
	v_xor_b32_e32 v20, 32, v19
	v_add_u32_e32 v21, 64, v21
	v_max3_f32 v18, v18, v12, v13
	v_cmp_lt_i32_e32 vcc, v20, v21
	v_max3_f32 v18, v18, v14, v15
	v_max3_f32 v18, v18, v16, v17
	v_cndmask_b32_e32 v19, v19, v20, vcc
	v_lshlrev_b32_e32 v19, 2, v19
	v_mov_b32_e32 v19, v18
	s_nop 1
	v_permlane32_swap_b32_e32 v19, v18
	s_nop 0
	s_mov_b32 s4, 0xf149f2ca
	s_mov_b32 s1, 0x3fb8aa3b
	v_max_f32_e32 v19, v19, v19
	v_max_f32_e32 v18, v18, v19
	v_mul_f32_e32 v18, 0x3fb8aa3b, v18
	v_max_f32_e32 v19, 0xf149f2ca, v18
	v_sub_f32_e32 v20, 0xf149f2ca, v19
	v_exp_f32_e32 v20, v20
	v_cmp_lt_f32_e32 vcc, s4, v18
	s_cmp_eq_u64 vcc, 0
	s_cselect_b64 vcc, -1, 0
	v_mul_f32_e32 v18, 0, v20
	v_cndmask_b32_e64 v50, v18, 0, vcc
	v_mov_b32_e32 v18, 0xf149f2ca
	v_cndmask_b32_e32 v116, v19, v18, vcc
	v_fma_f32 v2, v2, s1, -v116
	v_fma_f32 v3, v3, s1, -v116
	v_exp_f32_e32 v2, v2
	v_fma_f32 v4, v4, s1, -v116
	v_exp_f32_e32 v3, v3
	v_fma_f32 v5, v5, s1, -v116
	v_exp_f32_e32 v4, v4
	v_fma_f32 v6, v6, s1, -v116
	v_exp_f32_e32 v5, v5
	v_fma_f32 v7, v7, s1, -v116
	v_exp_f32_e32 v6, v6
	v_cndmask_b32_e64 v2, 0, v2, s[44:45]
	v_fma_f32 v8, v8, s1, -v116
	v_exp_f32_e32 v7, v7
	v_cndmask_b32_e64 v3, 0, v3, s[42:43]
	v_add_f32_e32 v18, 0, v2
	v_fma_f32 v9, v9, s1, -v116
	v_exp_f32_e32 v8, v8
	v_cndmask_b32_e64 v4, 0, v4, s[40:41]
	v_add_f32_e32 v18, v3, v18
	v_fma_f32 v10, v10, s1, -v116
	v_exp_f32_e32 v9, v9
	v_cndmask_b32_e64 v5, 0, v5, s[38:39]
	v_add_f32_e32 v18, v4, v18
	v_fma_f32 v11, v11, s1, -v116
	v_exp_f32_e32 v10, v10
	v_cndmask_b32_e64 v6, 0, v6, s[52:53]
	v_add_f32_e32 v18, v5, v18
	v_fma_f32 v12, v12, s1, -v116
	v_exp_f32_e32 v11, v11
	v_cndmask_b32_e64 v7, 0, v7, s[50:51]
	v_add_f32_e32 v18, v6, v18
	v_fma_f32 v13, v13, s1, -v116
	v_exp_f32_e32 v12, v12
	v_cndmask_b32_e64 v8, 0, v8, s[48:49]
	v_add_f32_e32 v18, v7, v18
	v_fma_f32 v14, v14, s1, -v116
	v_exp_f32_e32 v13, v13
	v_cndmask_b32_e64 v9, 0, v9, s[46:47]
	v_add_f32_e32 v18, v8, v18
	v_fma_f32 v15, v15, s1, -v116
	v_exp_f32_e32 v14, v14
	v_cndmask_b32_e64 v10, 0, v10, s[60:61]
	v_add_f32_e32 v18, v9, v18
	v_fma_f32 v16, v16, s1, -v116
	v_exp_f32_e32 v15, v15
	v_cndmask_b32_e64 v11, 0, v11, s[58:59]
	v_add_f32_e32 v18, v10, v18
	v_fma_f32 v17, v17, s1, -v116
	v_exp_f32_e32 v16, v16
	v_cndmask_b32_e64 v12, 0, v12, s[56:57]
	v_add_f32_e32 v18, v11, v18
	v_exp_f32_e32 v17, v17
	v_cndmask_b32_e64 v13, 0, v13, s[54:55]
	v_add_f32_e32 v18, v12, v18
	v_cndmask_b32_e64 v14, 0, v14, s[68:69]
	v_add_f32_e32 v18, v13, v18
	v_cndmask_b32_e64 v15, 0, v15, s[66:67]
	v_add_f32_e32 v18, v14, v18
	v_cndmask_b32_e64 v16, 0, v16, s[64:65]
	v_add_f32_e32 v18, v15, v18
	v_cndmask_b32_e64 v17, 0, v17, s[62:63]
	v_add_f32_e32 v18, v16, v18
	v_add_f32_e32 v115, v17, v18
	v_mov_b32_e32 v51, v50
	v_mov_b32_e32 v52, v50
	v_mov_b32_e32 v53, v50
	v_mov_b32_e32 v54, v50
	v_mov_b32_e32 v55, v50
	v_mov_b32_e32 v56, v50
	v_mov_b32_e32 v57, v50
	v_mov_b32_e32 v58, v50
	v_mov_b32_e32 v59, v50
	v_mov_b32_e32 v60, v50
	v_mov_b32_e32 v61, v50
	v_mov_b32_e32 v62, v50
	v_mov_b32_e32 v63, v50
	v_mov_b32_e32 v64, v50
	v_mov_b32_e32 v65, v50
	v_cvt_pk_bf16_f32 v118, v2, v3
	v_cvt_pk_bf16_f32 v119, v4, v5
	v_cvt_pk_bf16_f32 v120, v6, v7
	v_cvt_pk_bf16_f32 v121, v8, v9
	v_cvt_pk_bf16_f32 v122, v10, v11
	v_cvt_pk_bf16_f32 v123, v12, v13
	v_cvt_pk_bf16_f32 v124, v14, v15
	v_cvt_pk_bf16_f32 v125, v16, v17
	v_mov_b64_e32 v[18:19], v[50:51]
	v_mov_b64_e32 v[20:21], v[52:53]
	v_mov_b64_e32 v[22:23], v[54:55]
	v_mov_b64_e32 v[24:25], v[56:57]
	v_mov_b64_e32 v[26:27], v[58:59]
	v_mov_b64_e32 v[28:29], v[60:61]
	v_mov_b64_e32 v[30:31], v[62:63]
	v_mov_b64_e32 v[32:33], v[64:65]
	s_waitcnt lgkmcnt(0)
	v_mfma_f32_32x32x16_bf16 v[34:49], v[82:85], v[118:121], v[50:65]
	v_add_f32_e32 v115, v50, v115
	v_mfma_f32_32x32x16_bf16 v[18:33], v[94:97], v[118:121], v[18:33]
	v_mfma_f32_32x32x16_bf16 v[34:49], v[86:89], v[122:125], v[34:49]
	v_mfma_f32_32x32x16_bf16 v[18:33], v[90:93], v[122:125], v[18:33]
	s_cmp_ge_i32 s13, s18
	s_cselect_b64 s[4:5], -1, 0
	s_cmp_lt_i32 s13, s18
	s_cbranch_scc0 .LBB0_1005
	s_branch .LBB0_1006

.LBB0_1006:
	v_add_u32_e32 v50, v169, v165
	v_add_u32_e32 v51, v169, v166
	ds_read_b128 v[58:61], v50 offset:8192
	ds_read_b128 v[54:57], v51 offset:8192
	v_add_u32_e32 v50, v169, v163
	v_add_u32_e32 v51, v169, v164
	ds_read_b128 v[62:65], v50 offset:8192
	ds_read_b128 v[50:53], v51 offset:8192
	s_andn2_b64 vcc, exec, s[4:5]
	s_cbranch_vccnz .LBB0_1010
	s_waitcnt lgkmcnt(4)
	s_nop 0
	v_max_f32_e32 v98, v3, v3
	v_max_f32_e32 v99, v2, v2
	v_max_f32_e32 v98, v99, v98
	v_max3_f32 v98, v98, v4, v5
	v_max3_f32 v98, v98, v6, v7
	v_mbcnt_hi_u32_b32 v99, -1, v1
	v_max3_f32 v98, v98, v8, v9
	v_and_b32_e32 v101, 64, v99
	v_max3_f32 v98, v98, v10, v11
	v_xor_b32_e32 v100, 32, v99
	v_add_u32_e32 v101, 64, v101
	v_max3_f32 v98, v98, v12, v13
	v_cmp_lt_i32_e32 vcc, v100, v101
	v_max3_f32 v98, v98, v14, v15
	v_max3_f32 v98, v98, v16, v17
	v_cndmask_b32_e32 v99, v99, v100, vcc
	v_lshlrev_b32_e32 v99, 2, v99
	v_mov_b32_e32 v99, v98
	s_nop 1
	v_permlane32_swap_b32_e32 v99, v98
	s_nop 0
	s_mov_b32 s1, 0x3fb8aa3b
	v_max_f32_e32 v99, v99, v99
	v_max_f32_e32 v98, v98, v99
	v_mul_f32_e32 v98, 0x3fb8aa3b, v98
	v_add_f32_e32 v99, 0x41380000, v116
	v_cmp_gt_f32_e32 vcc, v98, v99
	s_cbranch_vccz .LBB0_1009
	v_max_f32_e32 v98, v98, v98
	v_max_f32_e32 v99, v116, v116
	v_max_f32_e32 v99, v99, v98
	v_sub_f32_e32 v98, v116, v99
	v_exp_f32_e32 v98, v98
	v_mov_b32_e32 v116, v99
	v_pk_mul_f32 v[48:49], v[48:49], v[98:99] op_sel_hi:[1,0]
	v_pk_mul_f32 v[46:47], v[46:47], v[98:99] op_sel_hi:[1,0]
	v_pk_mul_f32 v[44:45], v[44:45], v[98:99] op_sel_hi:[1,0]
	v_pk_mul_f32 v[42:43], v[42:43], v[98:99] op_sel_hi:[1,0]
	v_pk_mul_f32 v[40:41], v[40:41], v[98:99] op_sel_hi:[1,0]
	v_pk_mul_f32 v[38:39], v[38:39], v[98:99] op_sel_hi:[1,0]
	v_pk_mul_f32 v[36:37], v[36:37], v[98:99] op_sel_hi:[1,0]
	v_pk_mul_f32 v[34:35], v[34:35], v[98:99] op_sel_hi:[1,0]
	v_pk_mul_f32 v[32:33], v[32:33], v[98:99] op_sel_hi:[1,0]
	v_pk_mul_f32 v[30:31], v[30:31], v[98:99] op_sel_hi:[1,0]
	v_pk_mul_f32 v[28:29], v[28:29], v[98:99] op_sel_hi:[1,0]
	v_pk_mul_f32 v[26:27], v[26:27], v[98:99] op_sel_hi:[1,0]
	v_pk_mul_f32 v[24:25], v[24:25], v[98:99] op_sel_hi:[1,0]
	v_pk_mul_f32 v[22:23], v[22:23], v[98:99] op_sel_hi:[1,0]
	v_pk_mul_f32 v[20:21], v[20:21], v[98:99] op_sel_hi:[1,0]
	v_pk_mul_f32 v[18:19], v[18:19], v[98:99] op_sel_hi:[1,0]
	v_mul_f32_e32 v115, v115, v98
.LBB0_1009:
	v_fma_f32 v2, v2, s1, -v116
	v_fma_f32 v3, v3, s1, -v116
	v_exp_f32_e32 v2, v2
	v_fma_f32 v4, v4, s1, -v116
	v_exp_f32_e32 v3, v3
	v_fma_f32 v5, v5, s1, -v116
	v_exp_f32_e32 v4, v4
	v_fma_f32 v6, v6, s1, -v116
	v_exp_f32_e32 v5, v5
	v_fma_f32 v7, v7, s1, -v116
	v_exp_f32_e32 v6, v6
	v_add_f32_e32 v98, 0, v2
	v_fma_f32 v8, v8, s1, -v116
	v_exp_f32_e32 v7, v7
	v_add_f32_e32 v98, v3, v98
	v_fma_f32 v9, v9, s1, -v116
	v_exp_f32_e32 v8, v8
	v_add_f32_e32 v98, v4, v98
	v_fma_f32 v10, v10, s1, -v116
	v_exp_f32_e32 v9, v9
	v_add_f32_e32 v98, v5, v98
	v_fma_f32 v11, v11, s1, -v116
	v_exp_f32_e32 v10, v10
	v_add_f32_e32 v98, v6, v98
	v_fma_f32 v12, v12, s1, -v116
	v_exp_f32_e32 v11, v11
	v_add_f32_e32 v98, v7, v98
	v_fma_f32 v13, v13, s1, -v116
	v_exp_f32_e32 v12, v12
	v_add_f32_e32 v98, v8, v98
	v_fma_f32 v14, v14, s1, -v116
	v_exp_f32_e32 v13, v13
	v_add_f32_e32 v98, v9, v98
	v_fma_f32 v15, v15, s1, -v116
	v_exp_f32_e32 v14, v14
	v_add_f32_e32 v98, v10, v98
	v_fma_f32 v16, v16, s1, -v116
	v_exp_f32_e32 v15, v15
	v_add_f32_e32 v98, v11, v98
	v_fma_f32 v17, v17, s1, -v116
	v_exp_f32_e32 v16, v16
	v_add_f32_e32 v98, v12, v98
	v_exp_f32_e32 v17, v17
	v_add_f32_e32 v98, v13, v98
	v_add_f32_e32 v98, v14, v98
	v_add_f32_e32 v98, v15, v98
	v_add_f32_e32 v98, v16, v98
	v_add_f32_e32 v106, v17, v98
	v_cvt_pk_bf16_f32 v98, v2, v3
	v_cvt_pk_bf16_f32 v99, v4, v5
	v_cvt_pk_bf16_f32 v100, v6, v7
	v_cvt_pk_bf16_f32 v101, v8, v9
	v_cvt_pk_bf16_f32 v102, v10, v11
	v_cvt_pk_bf16_f32 v103, v12, v13
	v_cvt_pk_bf16_f32 v104, v14, v15
	v_cvt_pk_bf16_f32 v105, v16, v17
	s_waitcnt lgkmcnt(0)
	v_mfma_f32_32x32x16_bf16 v[34:49], v[82:85], v[98:101], v[34:49]
	v_add_f32_e32 v115, v115, v106
	v_mfma_f32_32x32x16_bf16 v[18:33], v[94:97], v[98:101], v[18:33]
	v_mfma_f32_32x32x16_bf16 v[34:49], v[86:89], v[102:105], v[34:49]
	v_mfma_f32_32x32x16_bf16 v[18:33], v[90:93], v[102:105], v[18:33]

.LBB0_1012:
	s_waitcnt lgkmcnt(0)
	v_add_u32_e32 v50, v168, v165
	v_add_u32_e32 v51, v168, v166
	ds_read_b128 v[58:61], v50 offset:8192
	ds_read_b128 v[54:57], v51 offset:8192
	v_add_u32_e32 v50, v168, v163
	v_add_u32_e32 v51, v168, v164
	ds_read_b128 v[62:65], v50 offset:8192
	ds_read_b128 v[50:53], v51 offset:8192
	s_andn2_b64 vcc, exec, s[4:5]
	s_cbranch_vccnz .LBB0_1016
	s_nop 0
	v_max_f32_e32 v98, v3, v3
	v_max_f32_e32 v99, v2, v2
	v_max_f32_e32 v98, v99, v98
	v_max3_f32 v98, v98, v4, v5
	v_max3_f32 v98, v98, v6, v7
	v_mbcnt_hi_u32_b32 v99, -1, v1
	v_max3_f32 v98, v98, v8, v9
	v_and_b32_e32 v101, 64, v99
	v_max3_f32 v98, v98, v10, v11
	v_xor_b32_e32 v100, 32, v99
	v_add_u32_e32 v101, 64, v101
	v_max3_f32 v98, v98, v12, v13
	v_cmp_lt_i32_e32 vcc, v100, v101
	v_max3_f32 v98, v98, v14, v15
	v_max3_f32 v98, v98, v16, v17
	v_cndmask_b32_e32 v99, v99, v100, vcc
	v_lshlrev_b32_e32 v99, 2, v99
	v_mov_b32_e32 v99, v98
	s_nop 1
	v_permlane32_swap_b32_e32 v99, v98
	s_nop 0
	s_mov_b32 s1, 0x3fb8aa3b
	v_max_f32_e32 v99, v99, v99
	v_max_f32_e32 v98, v98, v99
	v_mul_f32_e32 v98, 0x3fb8aa3b, v98
	v_add_f32_e32 v99, 0x41380000, v116
	v_cmp_gt_f32_e32 vcc, v98, v99
	s_cbranch_vccz .LBB0_1015
	v_max_f32_e32 v98, v98, v98
	v_max_f32_e32 v99, v116, v116
	v_max_f32_e32 v99, v99, v98
	v_sub_f32_e32 v98, v116, v99
	v_exp_f32_e32 v98, v98
	v_mov_b32_e32 v116, v99
	v_pk_mul_f32 v[48:49], v[48:49], v[98:99] op_sel_hi:[1,0]
	v_pk_mul_f32 v[46:47], v[46:47], v[98:99] op_sel_hi:[1,0]
	v_pk_mul_f32 v[44:45], v[44:45], v[98:99] op_sel_hi:[1,0]
	v_pk_mul_f32 v[42:43], v[42:43], v[98:99] op_sel_hi:[1,0]
	v_pk_mul_f32 v[40:41], v[40:41], v[98:99] op_sel_hi:[1,0]
	v_pk_mul_f32 v[38:39], v[38:39], v[98:99] op_sel_hi:[1,0]
	v_pk_mul_f32 v[36:37], v[36:37], v[98:99] op_sel_hi:[1,0]
	v_pk_mul_f32 v[34:35], v[34:35], v[98:99] op_sel_hi:[1,0]
	v_pk_mul_f32 v[32:33], v[32:33], v[98:99] op_sel_hi:[1,0]
	v_pk_mul_f32 v[30:31], v[30:31], v[98:99] op_sel_hi:[1,0]
	v_pk_mul_f32 v[28:29], v[28:29], v[98:99] op_sel_hi:[1,0]
	v_pk_mul_f32 v[26:27], v[26:27], v[98:99] op_sel_hi:[1,0]
	v_pk_mul_f32 v[24:25], v[24:25], v[98:99] op_sel_hi:[1,0]
	v_pk_mul_f32 v[22:23], v[22:23], v[98:99] op_sel_hi:[1,0]
	v_pk_mul_f32 v[20:21], v[20:21], v[98:99] op_sel_hi:[1,0]
	v_pk_mul_f32 v[18:19], v[18:19], v[98:99] op_sel_hi:[1,0]
	v_mul_f32_e32 v115, v115, v98

.LBB0_1018:
	s_waitcnt lgkmcnt(0)
	v_add_u32_e32 v50, v167, v165
	v_add_u32_e32 v51, v167, v166
	ds_read_b128 v[58:61], v50 offset:8192
	ds_read_b128 v[54:57], v51 offset:8192
	v_add_u32_e32 v50, v167, v163
	v_add_u32_e32 v51, v167, v164
	ds_read_b128 v[62:65], v50 offset:8192
	ds_read_b128 v[50:53], v51 offset:8192
	s_andn2_b64 vcc, exec, s[4:5]
	s_cbranch_vccnz .LBB0_1022
	s_nop 0
	v_max_f32_e32 v98, v3, v3
	v_max_f32_e32 v99, v2, v2
	v_max_f32_e32 v98, v99, v98
	v_max3_f32 v98, v98, v4, v5
	v_max3_f32 v98, v98, v6, v7
	v_mbcnt_hi_u32_b32 v99, -1, v1
	v_max3_f32 v98, v98, v8, v9
	v_and_b32_e32 v101, 64, v99
	v_max3_f32 v98, v98, v10, v11
	v_xor_b32_e32 v100, 32, v99
	v_add_u32_e32 v101, 64, v101
	v_max3_f32 v98, v98, v12, v13
	v_cmp_lt_i32_e32 vcc, v100, v101
	v_max3_f32 v98, v98, v14, v15
	v_max3_f32 v98, v98, v16, v17
	v_cndmask_b32_e32 v99, v99, v100, vcc
	v_lshlrev_b32_e32 v99, 2, v99
	v_mov_b32_e32 v99, v98
	s_nop 1
	v_permlane32_swap_b32_e32 v99, v98
	s_nop 0
	s_mov_b32 s1, 0x3fb8aa3b
	v_max_f32_e32 v99, v99, v99
	v_max_f32_e32 v98, v98, v99
	v_mul_f32_e32 v98, 0x3fb8aa3b, v98
	v_add_f32_e32 v99, 0x41380000, v116
	v_cmp_gt_f32_e32 vcc, v98, v99
	s_cbranch_vccz .LBB0_1021
	v_max_f32_e32 v98, v98, v98
	v_max_f32_e32 v99, v116, v116
	v_max_f32_e32 v99, v99, v98
	v_sub_f32_e32 v98, v116, v99
	v_exp_f32_e32 v98, v98
	v_mov_b32_e32 v116, v99
	v_pk_mul_f32 v[48:49], v[48:49], v[98:99] op_sel_hi:[1,0]
	v_pk_mul_f32 v[46:47], v[46:47], v[98:99] op_sel_hi:[1,0]
	v_pk_mul_f32 v[44:45], v[44:45], v[98:99] op_sel_hi:[1,0]
	v_pk_mul_f32 v[42:43], v[42:43], v[98:99] op_sel_hi:[1,0]
	v_pk_mul_f32 v[40:41], v[40:41], v[98:99] op_sel_hi:[1,0]
	v_pk_mul_f32 v[38:39], v[38:39], v[98:99] op_sel_hi:[1,0]
	v_pk_mul_f32 v[36:37], v[36:37], v[98:99] op_sel_hi:[1,0]
	v_pk_mul_f32 v[34:35], v[34:35], v[98:99] op_sel_hi:[1,0]
	v_pk_mul_f32 v[32:33], v[32:33], v[98:99] op_sel_hi:[1,0]
	v_pk_mul_f32 v[30:31], v[30:31], v[98:99] op_sel_hi:[1,0]
	v_pk_mul_f32 v[28:29], v[28:29], v[98:99] op_sel_hi:[1,0]
	v_pk_mul_f32 v[26:27], v[26:27], v[98:99] op_sel_hi:[1,0]
	v_pk_mul_f32 v[24:25], v[24:25], v[98:99] op_sel_hi:[1,0]
	v_pk_mul_f32 v[22:23], v[22:23], v[98:99] op_sel_hi:[1,0]
	v_pk_mul_f32 v[20:21], v[20:21], v[98:99] op_sel_hi:[1,0]
	v_pk_mul_f32 v[18:19], v[18:19], v[98:99] op_sel_hi:[1,0]
	v_mul_f32_e32 v115, v115, v98
